# FFN-up epilogue: hidden-activation (H) bf16 stores marked nt
# speedup vs baseline: 1.0043x; 1.0043x over previous
; __device__ __forceinline__ u32x4 pack8(const f32x4 a, const f32x4 b) { u32x4 w; w.x = cvt_pk_bf16(a[0], a[1]); w.y = cvt_pk_bf16(a[2], a[3]); w.z = cvt_pk_bf16(b[0], b[1]); w.w = cvt_pk_bf16(b[2], b[3]); return w; }
; __device__ __forceinline__ float rstd_of(ssq_t ss, float inv_n) { return __builtin_amdgcn_rsqf((float)ss * (1.0f / 16777216.0f) * inv_n + 1e-6f); }
; __device__ __forceinline__ float silu_mul2(float g, float u, float c1, float c2) { return (g * u) * (c2 * __builtin_amdgcn_rcpf(1.0f + __builtin_amdgcn_exp2f(g * c1))); }
;     __device__ __forceinline__ void operator()(const f32x4 (&acc)[2][2][4][2], const Unit& u, int wr, int wc, int fr, int fq) const {
;     ...
;             for (int m = 0; m < 4; ++m) { const int row = row0 + ai * HALF + m * 16; const float rs = rstd_of(ss[row], 1.0f / 2048.0f);
;                 const float c1 = -1.4426950408889634f * rs, c2 = rs * rs;
;                 f32x4 a0, a1;
; #pragma unroll
;                 for (int e = 0; e < 4; ++e) { a0[e] = silu_mul2(acc[ai][0][m][0][e], acc[ai][1][m][0][e], c1, c2); a1[e] = silu_mul2(acc[ai][0][m][1][e], acc[ai][1][m][1][e], c1, c2); }
;                 *(u32x4*)(H + (size_t)row * 5632 + col0) = pack8(a0, a1); }
.LBB0_501:
	v_lshl_add_u32 v144, s18, 8, v150
	v_ashrrev_i32_e32 v145, 31, v144
	v_lshl_add_u64 v[146:147], v[144:145], 3, s[6:7]
	global_load_dwordx2 v[158:159], v[146:147], off
	global_load_dwordx2 v[170:171], v[146:147], off offset:128
	global_load_dwordx2 v[172:173], v[146:147], off offset:256
	global_load_dwordx2 v[174:175], v[146:147], off offset:384
	global_load_dwordx2 v[176:177], v[146:147], off offset:1024
	global_load_dwordx2 v[178:179], v[146:147], off offset:1152
	global_load_dwordx2 v[180:181], v[146:147], off offset:1280
	global_load_dwordx2 v[182:183], v[146:147], off offset:1408
	v_pk_mul_f32 v[112:113], v[116:117], v[112:113]
	v_pk_mul_f32 v[114:115], v[118:119], v[114:115]
	v_pk_mul_f32 v[126:127], v[122:123], v[126:127]
	v_lshl_add_u32 v148, s51, 7, v152
	v_ashrrev_i32_e32 v149, 31, v148
	v_pk_mul_f32 v[96:97], v[100:101], v[96:97]
	v_pk_mul_f32 v[98:99], v[102:103], v[98:99]
	v_pk_mul_f32 v[110:111], v[106:107], v[110:111]
	v_pk_mul_f32 v[80:81], v[84:85], v[80:81]
	v_pk_mul_f32 v[82:83], v[86:87], v[82:83]
	v_pk_mul_f32 v[94:95], v[90:91], v[94:95]
	v_pk_mul_f32 v[64:65], v[68:69], v[64:65]
	v_pk_mul_f32 v[66:67], v[70:71], v[66:67]
	v_pk_mul_f32 v[78:79], v[74:75], v[78:79]
	v_pk_mul_f32 v[48:49], v[52:53], v[48:49]
	v_pk_mul_f32 v[50:51], v[54:55], v[50:51]
	v_pk_mul_f32 v[62:63], v[58:59], v[62:63]
	v_pk_mul_f32 v[32:33], v[36:37], v[32:33]
	v_pk_mul_f32 v[34:35], v[38:39], v[34:35]
	v_pk_mul_f32 v[46:47], v[42:43], v[46:47]
	v_pk_mul_f32 v[16:17], v[20:21], v[16:17]
	v_pk_mul_f32 v[18:19], v[22:23], v[18:19]
	v_pk_mul_f32 v[30:31], v[26:27], v[30:31]
	v_pk_mul_f32 v[0:1], v[4:5], v[0:1]
	v_pk_mul_f32 v[2:3], v[6:7], v[2:3]
	v_pk_mul_f32 v[14:15], v[10:11], v[14:15]
	s_andn2_b64 vcc, exec, s[0:1]
	s_waitcnt vmcnt(0)
	v_ffbh_u32_e32 v145, v159
	v_min_u32_e32 v145, 32, v145
	v_lshlrev_b64 v[158:159], v145, v[158:159]
	v_min_u32_e32 v157, 1, v158
	v_or_b32_e32 v157, v159, v157
	v_cvt_f32_u32_e32 v157, v157
	v_sub_u32_e32 v145, 32, v145
	v_ldexp_f32 v145, v157, v145
	v_mul_f32_e32 v145, 0x33800000, v145
	v_fmamk_f32 v145, v145, 0x3a000000, v156
	v_rsq_f32_e32 v145, v145
	s_nop 0
	v_mul_f32_e32 v157, 0xbfb8aa3b, v145
	v_mul_f32_e32 v158, v145, v145
	v_mul_f32_e32 v145, v120, v157
	v_exp_f32_e32 v145, v145
	s_nop 0
	v_add_f32_e32 v145, 1.0, v145
	v_rcp_f32_e32 v160, v145
	v_mul_f32_e32 v145, v116, v157
	v_exp_f32_e32 v145, v145
	s_nop 0
	v_add_f32_e32 v145, 1.0, v145
	v_rcp_f32_e32 v162, v145
	v_mul_f32_e32 v145, v121, v157
	v_exp_f32_e32 v145, v145
	v_pk_mul_f32 v[120:121], v[120:121], v[124:125]
	v_add_f32_e32 v145, 1.0, v145
	v_rcp_f32_e32 v161, v145
	s_nop 0
	v_pk_mul_f32 v[124:125], v[158:159], v[160:161] op_sel_hi:[0,1]
	v_pk_mul_f32 v[120:121], v[120:121], v[124:125]
	v_mul_f32_e32 v124, v117, v157
	v_exp_f32_e32 v124, v124
	s_nop 0
	v_add_f32_e32 v124, 1.0, v124
	v_rcp_f32_e32 v163, v124
	s_nop 0
	v_pk_mul_f32 v[116:117], v[158:159], v[162:163] op_sel_hi:[0,1]
	v_pk_mul_f32 v[112:113], v[112:113], v[116:117]
	v_mul_f32_e32 v117, v118, v157
	v_exp_f32_e32 v117, v117
	v_mul_f32_e32 v116, v122, v157
	v_exp_f32_e32 v116, v116
	v_add_f32_e32 v117, 1.0, v117
	v_rcp_f32_e32 v118, v117
	v_mul_f32_e32 v117, v123, v157
	v_exp_f32_e32 v117, v117
	v_add_f32_e32 v116, 1.0, v116
	v_rcp_f32_e32 v116, v116
	v_add_f32_e32 v117, 1.0, v117
	v_rcp_f32_e32 v117, v117
	s_nop 0
	v_pk_mul_f32 v[116:117], v[158:159], v[116:117] op_sel_hi:[0,1]
	v_pk_mul_f32 v[122:123], v[126:127], v[116:117]
	v_mul_f32_e32 v116, v119, v157
	v_exp_f32_e32 v116, v116
	s_nop 0
	v_add_f32_e32 v116, 1.0, v116
	v_rcp_f32_e32 v119, v116
	s_nop 0
	v_pk_mul_f32 v[116:117], v[158:159], v[118:119] op_sel_hi:[0,1]
	v_pk_mul_f32 v[114:115], v[114:115], v[116:117]
	v_cvt_pk_bf16_f32 v118, v112, v113
	v_mov_b64_e32 v[112:113], s[44:45]
	v_cvt_pk_bf16_f32 v116, v120, v121
	v_cvt_pk_bf16_f32 v119, v114, v115
	v_mad_i64_i32 v[120:121], s[4:5], v144, s50, v[112:113]
	v_lshlrev_b64 v[114:115], 1, v[148:149]
	v_cvt_pk_bf16_f32 v117, v122, v123
	v_lshl_add_u64 v[120:121], v[120:121], 0, v[114:115]
	global_store_dwordx4 v[120:121], v[116:119], off nt
	s_nop 1
	v_or_b32_e32 v116, 16, v144
	v_ashrrev_i32_e32 v117, 31, v116
	v_lshl_add_u64 v[118:119], v[116:117], 3, s[6:7]
	s_nop 1
	v_ffbh_u32_e32 v117, v171
	v_min_u32_e32 v117, 32, v117
	v_lshlrev_b64 v[118:119], v117, v[170:171]
	v_min_u32_e32 v118, 1, v118
	v_or_b32_e32 v118, v119, v118
	v_cvt_f32_u32_e32 v118, v118
	v_sub_u32_e32 v117, 32, v117
	v_ldexp_f32 v117, v118, v117
	v_mul_f32_e32 v117, 0x33800000, v117
	v_fmamk_f32 v117, v117, 0x3a000000, v156
	v_rsq_f32_e32 v117, v117
	s_nop 0
	v_mul_f32_e32 v119, 0xbfb8aa3b, v117
	v_mul_f32_e32 v118, v117, v117
	v_mul_f32_e32 v117, v104, v119
	v_exp_f32_e32 v117, v117
	s_nop 0
	v_add_f32_e32 v117, 1.0, v117
	v_rcp_f32_e32 v120, v117
	v_mul_f32_e32 v117, v100, v119
	v_exp_f32_e32 v117, v117
	s_nop 0
	v_add_f32_e32 v117, 1.0, v117
	v_rcp_f32_e32 v122, v117
	v_mul_f32_e32 v117, v105, v119
	v_exp_f32_e32 v117, v117
	v_pk_mul_f32 v[104:105], v[104:105], v[108:109]
	v_add_f32_e32 v117, 1.0, v117
	v_rcp_f32_e32 v121, v117
	s_nop 0
	v_pk_mul_f32 v[108:109], v[118:119], v[120:121] op_sel_hi:[0,1]
	v_pk_mul_f32 v[104:105], v[104:105], v[108:109]
	v_mul_f32_e32 v108, v101, v119
	v_exp_f32_e32 v108, v108
	s_nop 0
	v_add_f32_e32 v108, 1.0, v108
	v_rcp_f32_e32 v123, v108
	s_nop 0
	v_pk_mul_f32 v[100:101], v[118:119], v[122:123] op_sel_hi:[0,1]
	v_pk_mul_f32 v[100:101], v[96:97], v[100:101]
	v_mul_f32_e32 v97, v102, v119
	v_exp_f32_e32 v97, v97
	v_mul_f32_e32 v96, v106, v119
	v_exp_f32_e32 v96, v96
	v_add_f32_e32 v97, 1.0, v97
	v_rcp_f32_e32 v102, v97
	v_mul_f32_e32 v97, v107, v119
; __device__ __forceinline__ u32x4 pack8(const f32x4 a, const f32x4 b) { u32x4 w; w.x = cvt_pk_bf16(a[0], a[1]); w.y = cvt_pk_bf16(a[2], a[3]); w.z = cvt_pk_bf16(b[0], b[1]); w.w = cvt_pk_bf16(b[2], b[3]); return w; }
; __device__ __forceinline__ float rstd_of(ssq_t ss, float inv_n) { return __builtin_amdgcn_rsqf((float)ss * (1.0f / 16777216.0f) * inv_n + 1e-6f); }
; __device__ __forceinline__ float silu_mul2(float g, float u, float c1, float c2) { return (g * u) * (c2 * __builtin_amdgcn_rcpf(1.0f + __builtin_amdgcn_exp2f(g * c1))); }
;     __device__ __forceinline__ void operator()(const f32x4 (&acc)[2][2][4][2], const Unit& u, int wr, int wc, int fr, int fq) const {
;     ...
;             for (int m = 0; m < 4; ++m) { const int row = row0 + ai * HALF + m * 16; const float rs = rstd_of(ss[row], 1.0f / 2048.0f);
;                 const float c1 = -1.4426950408889634f * rs, c2 = rs * rs;
;                 f32x4 a0, a1;
; #pragma unroll
;                 for (int e = 0; e < 4; ++e) { a0[e] = silu_mul2(acc[ai][0][m][0][e], acc[ai][1][m][0][e], c1, c2); a1[e] = silu_mul2(acc[ai][0][m][1][e], acc[ai][1][m][1][e], c1, c2); }
;                 *(u32x4*)(H + (size_t)row * 5632 + col0) = pack8(a0, a1); }
	v_exp_f32_e32 v97, v97
	v_add_f32_e32 v96, 1.0, v96
	v_rcp_f32_e32 v96, v96
	v_add_f32_e32 v97, 1.0, v97
	v_rcp_f32_e32 v97, v97
	s_nop 0
	v_pk_mul_f32 v[96:97], v[118:119], v[96:97] op_sel_hi:[0,1]
	v_pk_mul_f32 v[106:107], v[110:111], v[96:97]
	v_mul_f32_e32 v96, v103, v119
	v_exp_f32_e32 v96, v96
	s_nop 0
	v_add_f32_e32 v96, 1.0, v96
	v_rcp_f32_e32 v103, v96
	s_nop 0
	v_pk_mul_f32 v[96:97], v[118:119], v[102:103] op_sel_hi:[0,1]
	v_pk_mul_f32 v[102:103], v[98:99], v[96:97]
	v_cvt_pk_bf16_f32 v98, v100, v101
	v_mad_i64_i32 v[100:101], s[4:5], v116, s50, v[112:113]
	v_cvt_pk_bf16_f32 v96, v104, v105
	v_cvt_pk_bf16_f32 v97, v106, v107
	v_cvt_pk_bf16_f32 v99, v102, v103
	v_lshl_add_u64 v[100:101], v[100:101], 0, v[114:115]
	global_store_dwordx4 v[100:101], v[96:99], off nt
	s_nop 1
	v_or_b32_e32 v96, 32, v144
	v_ashrrev_i32_e32 v97, 31, v96
	v_lshl_add_u64 v[98:99], v[96:97], 3, s[6:7]
	s_nop 1
	v_ffbh_u32_e32 v97, v173
	v_min_u32_e32 v97, 32, v97
	v_lshlrev_b64 v[98:99], v97, v[172:173]
	v_min_u32_e32 v98, 1, v98
	v_or_b32_e32 v98, v99, v98
	v_cvt_f32_u32_e32 v98, v98
	v_sub_u32_e32 v97, 32, v97
	v_ldexp_f32 v97, v98, v97
	v_mul_f32_e32 v97, 0x33800000, v97
	v_fmamk_f32 v97, v97, 0x3a000000, v156
	v_rsq_f32_e32 v97, v97
	s_nop 0
	v_mul_f32_e32 v99, 0xbfb8aa3b, v97
	v_mul_f32_e32 v98, v97, v97
	v_mul_f32_e32 v97, v88, v99
	v_exp_f32_e32 v97, v97
	s_nop 0
	v_add_f32_e32 v97, 1.0, v97
	v_rcp_f32_e32 v100, v97
	v_mul_f32_e32 v97, v84, v99
	v_exp_f32_e32 v97, v97
	s_nop 0
	v_add_f32_e32 v97, 1.0, v97
	v_rcp_f32_e32 v102, v97
	v_mul_f32_e32 v97, v89, v99
	v_exp_f32_e32 v97, v97
	v_pk_mul_f32 v[88:89], v[88:89], v[92:93]
	v_add_f32_e32 v97, 1.0, v97
	v_rcp_f32_e32 v101, v97
	s_nop 0
	v_pk_mul_f32 v[92:93], v[98:99], v[100:101] op_sel_hi:[0,1]
	v_pk_mul_f32 v[88:89], v[88:89], v[92:93]
	v_mul_f32_e32 v92, v85, v99
	v_exp_f32_e32 v92, v92
	s_nop 0
	v_add_f32_e32 v92, 1.0, v92
	v_rcp_f32_e32 v103, v92
	s_nop 0
	v_pk_mul_f32 v[84:85], v[98:99], v[102:103] op_sel_hi:[0,1]
	v_pk_mul_f32 v[84:85], v[80:81], v[84:85]
	v_mul_f32_e32 v81, v86, v99
	v_exp_f32_e32 v81, v81
	v_mul_f32_e32 v80, v90, v99
	v_exp_f32_e32 v80, v80
	v_add_f32_e32 v81, 1.0, v81
	v_rcp_f32_e32 v86, v81
	v_mul_f32_e32 v81, v91, v99
	v_exp_f32_e32 v81, v81
	v_add_f32_e32 v80, 1.0, v80
	v_rcp_f32_e32 v80, v80
	v_add_f32_e32 v81, 1.0, v81
	v_rcp_f32_e32 v81, v81
	s_nop 0
	v_pk_mul_f32 v[80:81], v[98:99], v[80:81] op_sel_hi:[0,1]
	v_pk_mul_f32 v[90:91], v[94:95], v[80:81]
	v_mul_f32_e32 v80, v87, v99
	v_exp_f32_e32 v80, v80
	s_nop 0
	v_add_f32_e32 v80, 1.0, v80
	v_rcp_f32_e32 v87, v80
	s_nop 0
	v_pk_mul_f32 v[80:81], v[98:99], v[86:87] op_sel_hi:[0,1]
	v_pk_mul_f32 v[86:87], v[82:83], v[80:81]
	v_cvt_pk_bf16_f32 v82, v84, v85
	v_mad_i64_i32 v[84:85], s[4:5], v96, s50, v[112:113]
	v_cvt_pk_bf16_f32 v80, v88, v89
	v_cvt_pk_bf16_f32 v81, v90, v91
	v_cvt_pk_bf16_f32 v83, v86, v87
	v_lshl_add_u64 v[84:85], v[84:85], 0, v[114:115]
	global_store_dwordx4 v[84:85], v[80:83], off nt
	s_nop 1
	v_or_b32_e32 v80, 48, v144
	v_ashrrev_i32_e32 v81, 31, v80
	v_lshl_add_u64 v[82:83], v[80:81], 3, s[6:7]
	s_nop 1
	v_ffbh_u32_e32 v81, v175
	v_min_u32_e32 v81, 32, v81
	v_lshlrev_b64 v[82:83], v81, v[174:175]
	v_min_u32_e32 v82, 1, v82
	v_or_b32_e32 v82, v83, v82
	v_cvt_f32_u32_e32 v82, v82
	v_sub_u32_e32 v81, 32, v81
	v_ldexp_f32 v81, v82, v81
	v_mul_f32_e32 v81, 0x33800000, v81
	v_fmamk_f32 v81, v81, 0x3a000000, v156
	v_rsq_f32_e32 v81, v81
	s_nop 0
	v_mul_f32_e32 v83, 0xbfb8aa3b, v81
	v_mul_f32_e32 v82, v81, v81
	v_mul_f32_e32 v81, v72, v83
	v_exp_f32_e32 v81, v81
	s_nop 0
	v_add_f32_e32 v81, 1.0, v81
	v_rcp_f32_e32 v84, v81
	v_mul_f32_e32 v81, v68, v83
	v_exp_f32_e32 v81, v81
	s_nop 0
	v_add_f32_e32 v81, 1.0, v81
	v_rcp_f32_e32 v86, v81
	v_mul_f32_e32 v81, v73, v83
	v_exp_f32_e32 v81, v81
	v_pk_mul_f32 v[72:73], v[72:73], v[76:77]
	v_add_f32_e32 v81, 1.0, v81
	v_rcp_f32_e32 v85, v81
	s_nop 0
	v_pk_mul_f32 v[76:77], v[82:83], v[84:85] op_sel_hi:[0,1]
	v_pk_mul_f32 v[72:73], v[72:73], v[76:77]
	v_mul_f32_e32 v76, v69, v83
	v_exp_f32_e32 v76, v76
	s_nop 0
	v_add_f32_e32 v76, 1.0, v76
	v_rcp_f32_e32 v87, v76
	s_nop 0
	v_pk_mul_f32 v[68:69], v[82:83], v[86:87] op_sel_hi:[0,1]
	v_pk_mul_f32 v[68:69], v[64:65], v[68:69]
	v_mul_f32_e32 v65, v70, v83
	v_exp_f32_e32 v65, v65
	v_mul_f32_e32 v64, v74, v83
	v_exp_f32_e32 v64, v64
	v_add_f32_e32 v65, 1.0, v65
	v_rcp_f32_e32 v70, v65
	v_mul_f32_e32 v65, v75, v83
	v_exp_f32_e32 v65, v65
	v_add_f32_e32 v64, 1.0, v64
	v_rcp_f32_e32 v64, v64
	v_add_f32_e32 v65, 1.0, v65
	v_rcp_f32_e32 v65, v65
	s_nop 0
	v_pk_mul_f32 v[64:65], v[82:83], v[64:65] op_sel_hi:[0,1]
	v_pk_mul_f32 v[74:75], v[78:79], v[64:65]
	v_mul_f32_e32 v64, v71, v83
	v_exp_f32_e32 v64, v64
	s_nop 0
	v_add_f32_e32 v64, 1.0, v64
	v_rcp_f32_e32 v71, v64
	s_nop 0
	v_pk_mul_f32 v[64:65], v[82:83], v[70:71] op_sel_hi:[0,1]
	v_pk_mul_f32 v[70:71], v[66:67], v[64:65]
	v_cvt_pk_bf16_f32 v66, v68, v69
	v_mad_i64_i32 v[68:69], s[4:5], v80, s50, v[112:113]
	v_cvt_pk_bf16_f32 v64, v72, v73
	v_cvt_pk_bf16_f32 v65, v74, v75
	v_cvt_pk_bf16_f32 v67, v70, v71
	v_lshl_add_u64 v[68:69], v[68:69], 0, v[114:115]
	global_store_dwordx4 v[68:69], v[64:67], off nt
	s_nop 1
	v_add_u32_e32 v70, 0x80, v144
	v_ffbh_u32_e32 v66, v177
	v_min_u32_e32 v66, 32, v66
	v_lshlrev_b64 v[64:65], v66, v[176:177]
	v_min_u32_e32 v64, 1, v64
	v_or_b32_e32 v64, v65, v64
	v_cvt_f32_u32_e32 v64, v64
	v_sub_u32_e32 v65, 32, v66
	v_ldexp_f32 v64, v64, v65
	v_mul_f32_e32 v64, 0x33800000, v64
	v_fmamk_f32 v64, v64, 0x3a000000, v156
	v_rsq_f32_e32 v64, v64
	s_nop 0
	v_mul_f32_e32 v65, 0xbfb8aa3b, v64
	v_mul_f32_e32 v67, v52, v65
	v_exp_f32_e32 v67, v67
; __device__ __forceinline__ u32x4 pack8(const f32x4 a, const f32x4 b) { u32x4 w; w.x = cvt_pk_bf16(a[0], a[1]); w.y = cvt_pk_bf16(a[2], a[3]); w.z = cvt_pk_bf16(b[0], b[1]); w.w = cvt_pk_bf16(b[2], b[3]); return w; }
; __device__ __forceinline__ float rstd_of(ssq_t ss, float inv_n) { return __builtin_amdgcn_rsqf((float)ss * (1.0f / 16777216.0f) * inv_n + 1e-6f); }
; __device__ __forceinline__ float silu_mul2(float g, float u, float c1, float c2) { return (g * u) * (c2 * __builtin_amdgcn_rcpf(1.0f + __builtin_amdgcn_exp2f(g * c1))); }
;     __device__ __forceinline__ void operator()(const f32x4 (&acc)[2][2][4][2], const Unit& u, int wr, int wc, int fr, int fq) const {
;     ...
;             for (int m = 0; m < 4; ++m) { const int row = row0 + ai * HALF + m * 16; const float rs = rstd_of(ss[row], 1.0f / 2048.0f);
;                 const float c1 = -1.4426950408889634f * rs, c2 = rs * rs;
;                 f32x4 a0, a1;
; #pragma unroll
;                 for (int e = 0; e < 4; ++e) { a0[e] = silu_mul2(acc[ai][0][m][0][e], acc[ai][1][m][0][e], c1, c2); a1[e] = silu_mul2(acc[ai][0][m][1][e], acc[ai][1][m][1][e], c1, c2); }
;                 *(u32x4*)(H + (size_t)row * 5632 + col0) = pack8(a0, a1); }
	v_mul_f32_e32 v66, v56, v65
	v_exp_f32_e32 v66, v66
	v_mul_f32_e32 v64, v64, v64
	v_add_f32_e32 v67, 1.0, v67
	v_rcp_f32_e32 v68, v67
	v_mul_f32_e32 v67, v57, v65
	v_exp_f32_e32 v67, v67
	v_add_f32_e32 v66, 1.0, v66
	v_rcp_f32_e32 v66, v66
	v_pk_mul_f32 v[56:57], v[56:57], v[60:61]
	v_add_f32_e32 v67, 1.0, v67
	v_rcp_f32_e32 v67, v67
	s_nop 0
	v_pk_mul_f32 v[60:61], v[64:65], v[66:67] op_sel_hi:[0,1]
	v_pk_mul_f32 v[56:57], v[56:57], v[60:61]
	v_mul_f32_e32 v60, v53, v65
	v_exp_f32_e32 v60, v60
	s_nop 0
	v_add_f32_e32 v60, 1.0, v60
	v_rcp_f32_e32 v69, v60
	s_nop 0
	v_pk_mul_f32 v[52:53], v[64:65], v[68:69] op_sel_hi:[0,1]
	v_pk_mul_f32 v[52:53], v[48:49], v[52:53]
	v_mul_f32_e32 v49, v54, v65
	v_exp_f32_e32 v49, v49
	v_mul_f32_e32 v48, v58, v65
	v_exp_f32_e32 v48, v48
	v_add_f32_e32 v49, 1.0, v49
	v_rcp_f32_e32 v54, v49
	v_mul_f32_e32 v49, v59, v65
	v_exp_f32_e32 v49, v49
	v_add_f32_e32 v48, 1.0, v48
	v_rcp_f32_e32 v48, v48
	v_add_f32_e32 v49, 1.0, v49
	v_rcp_f32_e32 v49, v49
	s_nop 0
	v_pk_mul_f32 v[48:49], v[64:65], v[48:49] op_sel_hi:[0,1]
	v_pk_mul_f32 v[58:59], v[62:63], v[48:49]
	v_mul_f32_e32 v48, v55, v65
	v_exp_f32_e32 v48, v48
	s_nop 0
	v_add_f32_e32 v48, 1.0, v48
	v_rcp_f32_e32 v55, v48
	s_nop 0
	v_pk_mul_f32 v[48:49], v[64:65], v[54:55] op_sel_hi:[0,1]
	v_pk_mul_f32 v[54:55], v[50:51], v[48:49]
	v_cvt_pk_bf16_f32 v50, v52, v53
	v_mad_i64_i32 v[52:53], s[4:5], v70, s50, v[112:113]
	v_cvt_pk_bf16_f32 v48, v56, v57
	v_cvt_pk_bf16_f32 v49, v58, v59
	v_cvt_pk_bf16_f32 v51, v54, v55
	v_lshl_add_u64 v[52:53], v[52:53], 0, v[114:115]
	global_store_dwordx4 v[52:53], v[48:51], off nt
	s_nop 1
	v_add_u32_e32 v54, 0x90, v144
	v_ffbh_u32_e32 v50, v179
	v_min_u32_e32 v50, 32, v50
	v_lshlrev_b64 v[48:49], v50, v[178:179]
	v_min_u32_e32 v48, 1, v48
	v_or_b32_e32 v48, v49, v48
	v_cvt_f32_u32_e32 v48, v48
	v_sub_u32_e32 v49, 32, v50
	v_ldexp_f32 v48, v48, v49
	v_mul_f32_e32 v48, 0x33800000, v48
	v_fmamk_f32 v48, v48, 0x3a000000, v156
	v_rsq_f32_e32 v48, v48
	s_nop 0
	v_mul_f32_e32 v49, 0xbfb8aa3b, v48
	v_mul_f32_e32 v51, v36, v49
	v_exp_f32_e32 v51, v51
	v_mul_f32_e32 v50, v40, v49
	v_exp_f32_e32 v50, v50
	v_mul_f32_e32 v48, v48, v48
	v_add_f32_e32 v51, 1.0, v51
	v_rcp_f32_e32 v52, v51
	v_mul_f32_e32 v51, v41, v49
	v_exp_f32_e32 v51, v51
	v_add_f32_e32 v50, 1.0, v50
	v_rcp_f32_e32 v50, v50
	v_pk_mul_f32 v[40:41], v[40:41], v[44:45]
	v_add_f32_e32 v51, 1.0, v51
	v_rcp_f32_e32 v51, v51
	s_nop 0
	v_pk_mul_f32 v[44:45], v[48:49], v[50:51] op_sel_hi:[0,1]
	v_pk_mul_f32 v[40:41], v[40:41], v[44:45]
	v_mul_f32_e32 v44, v37, v49
	v_exp_f32_e32 v44, v44
	s_nop 0
	v_add_f32_e32 v44, 1.0, v44
	v_rcp_f32_e32 v53, v44
	s_nop 0
	v_pk_mul_f32 v[36:37], v[48:49], v[52:53] op_sel_hi:[0,1]
	v_pk_mul_f32 v[36:37], v[32:33], v[36:37]
	v_mul_f32_e32 v33, v38, v49
	v_exp_f32_e32 v33, v33
	v_mul_f32_e32 v32, v42, v49
	v_exp_f32_e32 v32, v32
	v_add_f32_e32 v33, 1.0, v33
	v_rcp_f32_e32 v38, v33
	v_mul_f32_e32 v33, v43, v49
	v_exp_f32_e32 v33, v33
	v_add_f32_e32 v32, 1.0, v32
	v_rcp_f32_e32 v32, v32
	v_add_f32_e32 v33, 1.0, v33
	v_rcp_f32_e32 v33, v33
	s_nop 0
	v_pk_mul_f32 v[32:33], v[48:49], v[32:33] op_sel_hi:[0,1]
	v_pk_mul_f32 v[42:43], v[46:47], v[32:33]
	v_mul_f32_e32 v32, v39, v49
	v_exp_f32_e32 v32, v32
	s_nop 0
	v_add_f32_e32 v32, 1.0, v32
	v_rcp_f32_e32 v39, v32
	s_nop 0
	v_pk_mul_f32 v[32:33], v[48:49], v[38:39] op_sel_hi:[0,1]
	v_pk_mul_f32 v[38:39], v[34:35], v[32:33]
	v_cvt_pk_bf16_f32 v34, v36, v37
	v_mad_i64_i32 v[36:37], s[4:5], v54, s50, v[112:113]
	v_cvt_pk_bf16_f32 v32, v40, v41
	v_cvt_pk_bf16_f32 v33, v42, v43
	v_cvt_pk_bf16_f32 v35, v38, v39
	v_lshl_add_u64 v[36:37], v[36:37], 0, v[114:115]
	global_store_dwordx4 v[36:37], v[32:35], off nt
	s_nop 1
	v_add_u32_e32 v38, 0xa0, v144
	v_ffbh_u32_e32 v34, v181
	v_min_u32_e32 v34, 32, v34
	v_lshlrev_b64 v[32:33], v34, v[180:181]
	v_min_u32_e32 v32, 1, v32
	v_or_b32_e32 v32, v33, v32
	v_cvt_f32_u32_e32 v32, v32
	v_sub_u32_e32 v33, 32, v34
	v_ldexp_f32 v32, v32, v33
; __device__ __forceinline__ u32x4 pack8(const f32x4 a, const f32x4 b) { u32x4 w; w.x = cvt_pk_bf16(a[0], a[1]); w.y = cvt_pk_bf16(a[2], a[3]); w.z = cvt_pk_bf16(b[0], b[1]); w.w = cvt_pk_bf16(b[2], b[3]); return w; }
; __device__ __forceinline__ float rstd_of(ssq_t ss, float inv_n) { return __builtin_amdgcn_rsqf((float)ss * (1.0f / 16777216.0f) * inv_n + 1e-6f); }
; __device__ __forceinline__ float silu_mul2(float g, float u, float c1, float c2) { return (g * u) * (c2 * __builtin_amdgcn_rcpf(1.0f + __builtin_amdgcn_exp2f(g * c1))); }
;     __device__ __forceinline__ void operator()(const f32x4 (&acc)[2][2][4][2], const Unit& u, int wr, int wc, int fr, int fq) const {
;     ...
;             for (int m = 0; m < 4; ++m) { const int row = row0 + ai * HALF + m * 16; const float rs = rstd_of(ss[row], 1.0f / 2048.0f);
;                 const float c1 = -1.4426950408889634f * rs, c2 = rs * rs;
;                 f32x4 a0, a1;
; #pragma unroll
;                 for (int e = 0; e < 4; ++e) { a0[e] = silu_mul2(acc[ai][0][m][0][e], acc[ai][1][m][0][e], c1, c2); a1[e] = silu_mul2(acc[ai][0][m][1][e], acc[ai][1][m][1][e], c1, c2); }
;                 *(u32x4*)(H + (size_t)row * 5632 + col0) = pack8(a0, a1); }
	v_mul_f32_e32 v32, 0x33800000, v32
	v_fmamk_f32 v32, v32, 0x3a000000, v156
	v_rsq_f32_e32 v32, v32
	s_nop 0
	v_mul_f32_e32 v33, 0xbfb8aa3b, v32
	v_mul_f32_e32 v35, v20, v33
	v_exp_f32_e32 v35, v35
	v_mul_f32_e32 v34, v24, v33
	v_exp_f32_e32 v34, v34
	v_mul_f32_e32 v32, v32, v32
	v_add_f32_e32 v35, 1.0, v35
	v_rcp_f32_e32 v36, v35
	v_mul_f32_e32 v35, v25, v33
	v_exp_f32_e32 v35, v35
	v_add_f32_e32 v34, 1.0, v34
	v_rcp_f32_e32 v34, v34
	v_pk_mul_f32 v[24:25], v[24:25], v[28:29]
	v_add_f32_e32 v35, 1.0, v35
	v_rcp_f32_e32 v35, v35
	s_nop 0
	v_pk_mul_f32 v[28:29], v[32:33], v[34:35] op_sel_hi:[0,1]
	v_pk_mul_f32 v[24:25], v[24:25], v[28:29]
	v_mul_f32_e32 v28, v21, v33
	v_exp_f32_e32 v28, v28
	s_nop 0
	v_add_f32_e32 v28, 1.0, v28
	v_rcp_f32_e32 v37, v28
	s_nop 0
	v_pk_mul_f32 v[20:21], v[32:33], v[36:37] op_sel_hi:[0,1]
	v_pk_mul_f32 v[20:21], v[16:17], v[20:21]
	v_mul_f32_e32 v17, v22, v33
	v_exp_f32_e32 v17, v17
	v_mul_f32_e32 v16, v26, v33
	v_exp_f32_e32 v16, v16
	v_add_f32_e32 v17, 1.0, v17
	v_rcp_f32_e32 v22, v17
	v_mul_f32_e32 v17, v27, v33
	v_exp_f32_e32 v17, v17
	v_add_f32_e32 v16, 1.0, v16
	v_rcp_f32_e32 v16, v16
	v_add_f32_e32 v17, 1.0, v17
	v_rcp_f32_e32 v17, v17
	s_nop 0
	v_pk_mul_f32 v[16:17], v[32:33], v[16:17] op_sel_hi:[0,1]
	v_pk_mul_f32 v[26:27], v[30:31], v[16:17]
	v_mul_f32_e32 v16, v23, v33
	v_exp_f32_e32 v16, v16
	s_nop 0
	v_add_f32_e32 v16, 1.0, v16
	v_rcp_f32_e32 v23, v16
	s_nop 0
	v_pk_mul_f32 v[16:17], v[32:33], v[22:23] op_sel_hi:[0,1]
	v_pk_mul_f32 v[22:23], v[18:19], v[16:17]
	v_cvt_pk_bf16_f32 v18, v20, v21
	v_mad_i64_i32 v[20:21], s[4:5], v38, s50, v[112:113]
	v_cvt_pk_bf16_f32 v16, v24, v25
	v_cvt_pk_bf16_f32 v17, v26, v27
	v_cvt_pk_bf16_f32 v19, v22, v23
	v_lshl_add_u64 v[20:21], v[20:21], 0, v[114:115]
	global_store_dwordx4 v[20:21], v[16:19], off nt
	s_nop 1
	v_add_u32_e32 v22, 0xb0, v144
	v_ffbh_u32_e32 v18, v183
	v_min_u32_e32 v18, 32, v18
	v_lshlrev_b64 v[16:17], v18, v[182:183]
	v_min_u32_e32 v16, 1, v16
	v_or_b32_e32 v16, v17, v16
	v_cvt_f32_u32_e32 v16, v16
	v_sub_u32_e32 v17, 32, v18
	v_ldexp_f32 v16, v16, v17
	v_mul_f32_e32 v16, 0x33800000, v16
	v_fmamk_f32 v16, v16, 0x3a000000, v156
	v_rsq_f32_e32 v16, v16
	s_nop 0
	v_mul_f32_e32 v17, 0xbfb8aa3b, v16
	v_mul_f32_e32 v19, v4, v17
	v_exp_f32_e32 v19, v19
	v_mul_f32_e32 v18, v8, v17
	v_exp_f32_e32 v18, v18
	v_mul_f32_e32 v16, v16, v16
	v_add_f32_e32 v19, 1.0, v19
	v_rcp_f32_e32 v20, v19
	v_mul_f32_e32 v19, v9, v17
	v_exp_f32_e32 v19, v19
	v_add_f32_e32 v18, 1.0, v18
	v_rcp_f32_e32 v18, v18
	v_pk_mul_f32 v[8:9], v[8:9], v[12:13]
	v_add_f32_e32 v19, 1.0, v19
	v_rcp_f32_e32 v19, v19
	s_nop 0
	v_pk_mul_f32 v[12:13], v[16:17], v[18:19] op_sel_hi:[0,1]
	v_pk_mul_f32 v[8:9], v[8:9], v[12:13]
	v_mul_f32_e32 v12, v5, v17
	v_exp_f32_e32 v12, v12
	s_nop 0
	v_add_f32_e32 v12, 1.0, v12
	v_rcp_f32_e32 v21, v12
	s_nop 0
	v_pk_mul_f32 v[4:5], v[16:17], v[20:21] op_sel_hi:[0,1]
	v_pk_mul_f32 v[4:5], v[0:1], v[4:5]
	v_mul_f32_e32 v1, v6, v17
	v_exp_f32_e32 v1, v1
	v_mul_f32_e32 v0, v10, v17
	v_exp_f32_e32 v0, v0
	v_add_f32_e32 v1, 1.0, v1
	v_rcp_f32_e32 v6, v1
	v_mul_f32_e32 v1, v11, v17
	v_exp_f32_e32 v1, v1
	v_add_f32_e32 v0, 1.0, v0
	v_rcp_f32_e32 v0, v0
	v_add_f32_e32 v1, 1.0, v1
	v_rcp_f32_e32 v1, v1
	s_nop 0
	v_pk_mul_f32 v[0:1], v[16:17], v[0:1] op_sel_hi:[0,1]
	v_pk_mul_f32 v[10:11], v[14:15], v[0:1]
	v_mul_f32_e32 v0, v7, v17
	v_exp_f32_e32 v0, v0
	s_nop 0
	v_add_f32_e32 v0, 1.0, v0
	v_rcp_f32_e32 v7, v0
	s_nop 0
	v_pk_mul_f32 v[0:1], v[16:17], v[6:7] op_sel_hi:[0,1]
	v_pk_mul_f32 v[6:7], v[2:3], v[0:1]
	v_cvt_pk_bf16_f32 v2, v4, v5
	v_mad_i64_i32 v[4:5], s[4:5], v22, s50, v[112:113]
	v_cvt_pk_bf16_f32 v0, v8, v9
	v_cvt_pk_bf16_f32 v1, v10, v11
	v_cvt_pk_bf16_f32 v3, v6, v7
	v_lshl_add_u64 v[4:5], v[4:5], 0, v[114:115]
	s_mov_b64 s[4:5], -1
	global_store_dwordx4 v[4:5], v[0:3], off nt
	s_cbranch_vccnz .LBB0_494
	s_andn2_b64 vcc, exec, s[2:3]
	s_cbranch_vccnz .LBB0_493
	s_barrier
	s_branch .LBB0_493

; __device__ __forceinline__ u32x4 pack8(const f32x4 a, const f32x4 b) { u32x4 w; w.x = cvt_pk_bf16(a[0], a[1]); w.y = cvt_pk_bf16(a[2], a[3]); w.z = cvt_pk_bf16(b[0], b[1]); w.w = cvt_pk_bf16(b[2], b[3]); return w; }
; __device__ __forceinline__ float rstd_of(ssq_t ss, float inv_n) { return __builtin_amdgcn_rsqf((float)ss * (1.0f / 16777216.0f) * inv_n + 1e-6f); }
; __device__ __forceinline__ float silu_mul2(float g, float u, float c1, float c2) { return (g * u) * (c2 * __builtin_amdgcn_rcpf(1.0f + __builtin_amdgcn_exp2f(g * c1))); }
;     __device__ __forceinline__ void operator()(const f32x4 (&acc)[2][2][4][2], const Unit& u, int wr, int wc, int fr, int fq) const {
;     ...
;             for (int m = 0; m < 4; ++m) { const int row = row0 + ai * HALF + m * 16; const float rs = rstd_of(ss[row], 1.0f / 2048.0f);
;                 const float c1 = -1.4426950408889634f * rs, c2 = rs * rs;
;                 f32x4 a0, a1;
; #pragma unroll
;                 for (int e = 0; e < 4; ++e) { a0[e] = silu_mul2(acc[ai][0][m][0][e], acc[ai][1][m][0][e], c1, c2); a1[e] = silu_mul2(acc[ai][0][m][1][e], acc[ai][1][m][1][e], c1, c2); }
;                 *(u32x4*)(H + (size_t)row * 5632 + col0) = pack8(a0, a1); }
.LBB0_1393:
	v_lshl_add_u32 v144, s60, 8, v148
	v_ashrrev_i32_e32 v145, 31, v144
	v_lshl_add_u64 v[146:147], v[144:145], 3, s[4:5]
	global_load_dwordx2 v[156:157], v[146:147], off
	global_load_dwordx2 v[170:171], v[146:147], off offset:128
	global_load_dwordx2 v[172:173], v[146:147], off offset:256
	global_load_dwordx2 v[174:175], v[146:147], off offset:384
	global_load_dwordx2 v[176:177], v[146:147], off offset:1024
	global_load_dwordx2 v[178:179], v[146:147], off offset:1152
	global_load_dwordx2 v[180:181], v[146:147], off offset:1280
	global_load_dwordx2 v[182:183], v[146:147], off offset:1408
	v_pk_mul_f32 v[160:161], v[114:115], v[122:123]
	v_pk_mul_f32 v[126:127], v[118:119], v[126:127]
	v_pk_mul_f32 v[124:125], v[116:117], v[124:125]
	v_pk_mul_f32 v[162:163], v[112:113], v[120:121]
	v_lshl_add_u32 v158, s73, 7, v150
	v_mov_b64_e32 v[120:121], s[44:45]
	v_ashrrev_i32_e32 v159, 31, v158
	v_mad_i64_i32 v[164:165], s[62:63], v144, s72, v[120:121]
	v_pk_mul_f32 v[110:111], v[102:103], v[110:111]
	v_pk_mul_f32 v[108:109], v[100:101], v[108:109]
	v_pk_mul_f32 v[106:107], v[98:99], v[106:107]
	v_pk_mul_f32 v[104:105], v[96:97], v[104:105]
	v_pk_mul_f32 v[94:95], v[86:87], v[94:95]
	v_pk_mul_f32 v[92:93], v[84:85], v[92:93]
	v_pk_mul_f32 v[90:91], v[82:83], v[90:91]
	v_pk_mul_f32 v[88:89], v[80:81], v[88:89]
	v_pk_mul_f32 v[78:79], v[70:71], v[78:79]
	v_pk_mul_f32 v[76:77], v[68:69], v[76:77]
	v_pk_mul_f32 v[74:75], v[66:67], v[74:75]
	v_pk_mul_f32 v[72:73], v[64:65], v[72:73]
	v_pk_mul_f32 v[62:63], v[54:55], v[62:63]
	v_pk_mul_f32 v[60:61], v[52:53], v[60:61]
	v_pk_mul_f32 v[58:59], v[50:51], v[58:59]
	v_pk_mul_f32 v[56:57], v[48:49], v[56:57]
	v_pk_mul_f32 v[46:47], v[38:39], v[46:47]
	v_pk_mul_f32 v[44:45], v[36:37], v[44:45]
	v_pk_mul_f32 v[42:43], v[34:35], v[42:43]
	v_pk_mul_f32 v[40:41], v[32:33], v[40:41]
	v_pk_mul_f32 v[30:31], v[22:23], v[30:31]
	v_pk_mul_f32 v[28:29], v[20:21], v[28:29]
	v_pk_mul_f32 v[26:27], v[18:19], v[26:27]
	v_pk_mul_f32 v[24:25], v[16:17], v[24:25]
	v_pk_mul_f32 v[14:15], v[6:7], v[14:15]
	v_pk_mul_f32 v[12:13], v[4:5], v[12:13]
	v_pk_mul_f32 v[10:11], v[2:3], v[10:11]
	v_pk_mul_f32 v[8:9], v[0:1], v[8:9]
	s_andn2_b64 vcc, exec, s[2:3]
	s_mov_b64 s[2:3], -1
	s_waitcnt vmcnt(0)
	v_ffbh_u32_e32 v122, v157
	v_min_u32_e32 v145, 32, v122
	v_lshlrev_b64 v[122:123], v145, v[156:157]
	v_min_u32_e32 v122, 1, v122
	v_or_b32_e32 v122, v123, v122
	v_cvt_f32_u32_e32 v155, v122
	v_sub_u32_e32 v145, 32, v145
	v_or_b32_e32 v156, 16, v144
	v_lshlrev_b64 v[122:123], 1, v[158:159]
	v_ldexp_f32 v145, v155, v145
	v_mul_f32_e32 v145, 0x33800000, v145
	v_fmamk_f32 v145, v145, 0x3a000000, v154
	v_rsq_f32_e32 v145, v145
	v_ashrrev_i32_e32 v157, 31, v156
	v_lshl_add_u64 v[158:159], v[164:165], 0, v[122:123]
	v_lshl_add_u64 v[164:165], v[156:157], 3, s[4:5]
	v_mul_f32_e32 v155, 0xbfb8aa3b, v145
	v_mul_f32_e32 v116, v116, v155
	v_mul_f32_e32 v112, v112, v155
	v_mul_f32_e32 v117, v117, v155
	v_mul_f32_e32 v113, v113, v155
	v_mul_f32_e32 v118, v118, v155
	v_mul_f32_e32 v114, v114, v155
	v_mul_f32_e32 v119, v119, v155
	v_mul_f32_e32 v115, v115, v155
	v_exp_f32_e32 v116, v116
	v_exp_f32_e32 v112, v112
	v_exp_f32_e32 v117, v117
	v_exp_f32_e32 v113, v113
	v_exp_f32_e32 v118, v118
	v_exp_f32_e32 v114, v114
	v_exp_f32_e32 v119, v119
	v_exp_f32_e32 v115, v115
	v_mul_f32_e32 v166, v145, v145
	v_add_f32_e32 v116, 1.0, v116
	v_add_f32_e32 v145, 1.0, v112
	v_add_f32_e32 v117, 1.0, v117
	v_add_f32_e32 v155, 1.0, v113
	v_add_f32_e32 v118, 1.0, v118
	v_add_f32_e32 v157, 1.0, v114
	v_add_f32_e32 v119, 1.0, v119
	v_add_f32_e32 v167, 1.0, v115
	v_rcp_f32_e32 v112, v116
	v_rcp_f32_e32 v114, v145
	v_rcp_f32_e32 v113, v117
	v_rcp_f32_e32 v115, v155
	v_rcp_f32_e32 v116, v118
	v_rcp_f32_e32 v118, v157
	v_rcp_f32_e32 v117, v119
	v_rcp_f32_e32 v119, v167
	v_pk_mul_f32 v[112:113], v[166:167], v[112:113] op_sel_hi:[0,1]
	v_pk_mul_f32 v[114:115], v[166:167], v[114:115] op_sel_hi:[0,1]
	v_pk_mul_f32 v[116:117], v[166:167], v[116:117] op_sel_hi:[0,1]
	v_pk_mul_f32 v[118:119], v[166:167], v[118:119] op_sel_hi:[0,1]
	v_pk_mul_f32 v[112:113], v[124:125], v[112:113]
	v_pk_mul_f32 v[114:115], v[162:163], v[114:115]
	v_pk_mul_f32 v[116:117], v[126:127], v[116:117]
	v_pk_mul_f32 v[118:119], v[160:161], v[118:119]
	v_cvt_pk_bf16_f32 v112, v112, v113
	v_cvt_pk_bf16_f32 v113, v116, v117
	v_cvt_pk_bf16_f32 v114, v114, v115
	v_cvt_pk_bf16_f32 v115, v118, v119
	global_store_dwordx4 v[158:159], v[112:115], off nt
	s_nop 1
	s_nop 0
	v_or_b32_e32 v114, 32, v144
	v_ffbh_u32_e32 v115, v171
	v_min_u32_e32 v115, 32, v115
	v_lshlrev_b64 v[112:113], v115, v[170:171]
	v_min_u32_e32 v112, 1, v112
	v_or_b32_e32 v112, v113, v112
	v_cvt_f32_u32_e32 v116, v112
	v_sub_u32_e32 v115, 32, v115
	v_mad_i64_i32 v[112:113], s[62:63], v156, s72, v[120:121]
	v_ldexp_f32 v115, v116, v115
	v_mul_f32_e32 v115, 0x33800000, v115
	v_fmamk_f32 v115, v115, 0x3a000000, v154
	v_rsq_f32_e32 v118, v115
	v_ashrrev_i32_e32 v115, 31, v114
	v_lshl_add_u64 v[116:117], v[114:115], 3, s[4:5]
	v_lshl_add_u64 v[112:113], v[112:113], 0, v[122:123]
	v_mul_f32_e32 v115, 0xbfb8aa3b, v118
	v_mul_f32_e32 v100, v100, v115
	v_mul_f32_e32 v96, v96, v115
	v_mul_f32_e32 v101, v101, v115
	v_mul_f32_e32 v97, v97, v115
	v_mul_f32_e32 v102, v102, v115
	v_mul_f32_e32 v98, v98, v115
	v_mul_f32_e32 v103, v103, v115
	v_mul_f32_e32 v99, v99, v115
	v_exp_f32_e32 v100, v100
	v_exp_f32_e32 v96, v96
	v_exp_f32_e32 v101, v101
	v_exp_f32_e32 v97, v97
	v_exp_f32_e32 v102, v102
	v_exp_f32_e32 v98, v98
	v_exp_f32_e32 v103, v103
	v_exp_f32_e32 v99, v99
	v_add_f32_e32 v100, 1.0, v100
	v_add_f32_e32 v115, 1.0, v96
	v_add_f32_e32 v101, 1.0, v101
; __device__ __forceinline__ u32x4 pack8(const f32x4 a, const f32x4 b) { u32x4 w; w.x = cvt_pk_bf16(a[0], a[1]); w.y = cvt_pk_bf16(a[2], a[3]); w.z = cvt_pk_bf16(b[0], b[1]); w.w = cvt_pk_bf16(b[2], b[3]); return w; }
; __device__ __forceinline__ float rstd_of(ssq_t ss, float inv_n) { return __builtin_amdgcn_rsqf((float)ss * (1.0f / 16777216.0f) * inv_n + 1e-6f); }
; __device__ __forceinline__ float silu_mul2(float g, float u, float c1, float c2) { return (g * u) * (c2 * __builtin_amdgcn_rcpf(1.0f + __builtin_amdgcn_exp2f(g * c1))); }
;     __device__ __forceinline__ void operator()(const f32x4 (&acc)[2][2][4][2], const Unit& u, int wr, int wc, int fr, int fq) const {
;     ...
;             for (int m = 0; m < 4; ++m) { const int row = row0 + ai * HALF + m * 16; const float rs = rstd_of(ss[row], 1.0f / 2048.0f);
;                 const float c1 = -1.4426950408889634f * rs, c2 = rs * rs;
;                 f32x4 a0, a1;
; #pragma unroll
;                 for (int e = 0; e < 4; ++e) { a0[e] = silu_mul2(acc[ai][0][m][0][e], acc[ai][1][m][0][e], c1, c2); a1[e] = silu_mul2(acc[ai][0][m][1][e], acc[ai][1][m][1][e], c1, c2); }
;                 *(u32x4*)(H + (size_t)row * 5632 + col0) = pack8(a0, a1); }
	v_add_f32_e32 v119, 1.0, v97
	v_add_f32_e32 v102, 1.0, v102
	v_add_f32_e32 v124, 1.0, v98
	v_add_f32_e32 v103, 1.0, v103
	v_add_f32_e32 v125, 1.0, v99
	v_rcp_f32_e32 v96, v100
	v_rcp_f32_e32 v98, v115
	v_rcp_f32_e32 v97, v101
	v_rcp_f32_e32 v99, v119
	v_rcp_f32_e32 v100, v102
	v_rcp_f32_e32 v102, v124
	v_rcp_f32_e32 v101, v103
	v_rcp_f32_e32 v103, v125
	v_mul_f32_e32 v118, v118, v118
	v_pk_mul_f32 v[96:97], v[118:119], v[96:97] op_sel_hi:[0,1]
	v_pk_mul_f32 v[98:99], v[118:119], v[98:99] op_sel_hi:[0,1]
	v_pk_mul_f32 v[100:101], v[118:119], v[100:101] op_sel_hi:[0,1]
	v_pk_mul_f32 v[102:103], v[118:119], v[102:103] op_sel_hi:[0,1]
	v_pk_mul_f32 v[96:97], v[108:109], v[96:97]
	v_pk_mul_f32 v[98:99], v[104:105], v[98:99]
	v_pk_mul_f32 v[100:101], v[110:111], v[100:101]
	v_pk_mul_f32 v[102:103], v[106:107], v[102:103]
	v_cvt_pk_bf16_f32 v96, v96, v97
	v_cvt_pk_bf16_f32 v97, v100, v101
	v_cvt_pk_bf16_f32 v98, v98, v99
	v_cvt_pk_bf16_f32 v99, v102, v103
	global_store_dwordx4 v[112:113], v[96:99], off nt
	s_nop 1
	s_nop 0
	v_or_b32_e32 v98, 48, v144
	v_ffbh_u32_e32 v99, v173
	v_min_u32_e32 v99, 32, v99
	v_lshlrev_b64 v[96:97], v99, v[172:173]
	v_min_u32_e32 v96, 1, v96
	v_or_b32_e32 v96, v97, v96
	v_cvt_f32_u32_e32 v100, v96
	v_sub_u32_e32 v99, 32, v99
	v_mad_i64_i32 v[96:97], s[62:63], v114, s72, v[120:121]
	v_ldexp_f32 v99, v100, v99
	v_mul_f32_e32 v99, 0x33800000, v99
	v_fmamk_f32 v99, v99, 0x3a000000, v154
	v_rsq_f32_e32 v102, v99
	v_ashrrev_i32_e32 v99, 31, v98
	v_lshl_add_u64 v[100:101], v[98:99], 3, s[4:5]
	v_lshl_add_u64 v[96:97], v[96:97], 0, v[122:123]
	v_mul_f32_e32 v99, 0xbfb8aa3b, v102
	v_mul_f32_e32 v84, v84, v99
	v_mul_f32_e32 v80, v80, v99
	v_mul_f32_e32 v85, v85, v99
	v_mul_f32_e32 v81, v81, v99
	v_mul_f32_e32 v86, v86, v99
	v_mul_f32_e32 v82, v82, v99
	v_mul_f32_e32 v87, v87, v99
	v_mul_f32_e32 v83, v83, v99
	v_exp_f32_e32 v84, v84
	v_exp_f32_e32 v80, v80
	v_exp_f32_e32 v85, v85
	v_exp_f32_e32 v81, v81
	v_exp_f32_e32 v86, v86
	v_exp_f32_e32 v82, v82
	v_exp_f32_e32 v87, v87
	v_exp_f32_e32 v83, v83
	v_add_f32_e32 v84, 1.0, v84
	v_add_f32_e32 v99, 1.0, v80
	v_add_f32_e32 v85, 1.0, v85
	v_add_f32_e32 v103, 1.0, v81
	v_add_f32_e32 v86, 1.0, v86
	v_add_f32_e32 v104, 1.0, v82
	v_add_f32_e32 v87, 1.0, v87
	v_add_f32_e32 v105, 1.0, v83
	v_rcp_f32_e32 v80, v84
	v_rcp_f32_e32 v82, v99
	v_rcp_f32_e32 v81, v85
	v_rcp_f32_e32 v83, v103
	v_rcp_f32_e32 v84, v86
	v_rcp_f32_e32 v86, v104
	v_rcp_f32_e32 v85, v87
	v_rcp_f32_e32 v87, v105
	v_mul_f32_e32 v102, v102, v102
	v_pk_mul_f32 v[80:81], v[102:103], v[80:81] op_sel_hi:[0,1]
	v_pk_mul_f32 v[82:83], v[102:103], v[82:83] op_sel_hi:[0,1]
	v_pk_mul_f32 v[84:85], v[102:103], v[84:85] op_sel_hi:[0,1]
	v_pk_mul_f32 v[86:87], v[102:103], v[86:87] op_sel_hi:[0,1]
	v_pk_mul_f32 v[80:81], v[92:93], v[80:81]
	v_pk_mul_f32 v[82:83], v[88:89], v[82:83]
	v_pk_mul_f32 v[84:85], v[94:95], v[84:85]
	v_pk_mul_f32 v[86:87], v[90:91], v[86:87]
	v_cvt_pk_bf16_f32 v80, v80, v81
	v_cvt_pk_bf16_f32 v81, v84, v85
	v_cvt_pk_bf16_f32 v82, v82, v83
	v_cvt_pk_bf16_f32 v83, v86, v87
	global_store_dwordx4 v[96:97], v[80:83], off nt
	s_nop 1
	v_ffbh_u32_e32 v82, v175
	v_min_u32_e32 v82, 32, v82
	v_lshlrev_b64 v[80:81], v82, v[174:175]
	v_min_u32_e32 v80, 1, v80
	v_or_b32_e32 v80, v81, v80
	v_cvt_f32_u32_e32 v80, v80
	v_sub_u32_e32 v81, 32, v82
	v_ldexp_f32 v80, v80, v81
	v_mul_f32_e32 v80, 0x33800000, v80
	v_fmamk_f32 v80, v80, 0x3a000000, v154
	v_rsq_f32_e32 v82, v80
	v_mad_i64_i32 v[80:81], s[62:63], v98, s72, v[120:121]
	v_lshl_add_u64 v[80:81], v[80:81], 0, v[122:123]
	v_mul_f32_e32 v83, 0xbfb8aa3b, v82
	v_mul_f32_e32 v68, v68, v83
	v_mul_f32_e32 v64, v64, v83
	v_mul_f32_e32 v69, v69, v83
	v_mul_f32_e32 v65, v65, v83
	v_mul_f32_e32 v70, v70, v83
	v_mul_f32_e32 v66, v66, v83
	v_mul_f32_e32 v71, v71, v83
	v_mul_f32_e32 v67, v67, v83
	v_exp_f32_e32 v68, v68
	v_exp_f32_e32 v64, v64
	v_exp_f32_e32 v69, v69
	v_exp_f32_e32 v65, v65
	v_exp_f32_e32 v70, v70
	v_exp_f32_e32 v66, v66
	v_exp_f32_e32 v71, v71
	v_exp_f32_e32 v67, v67
	v_add_f32_e32 v68, 1.0, v68
	v_add_f32_e32 v83, 1.0, v64
	v_add_f32_e32 v69, 1.0, v69
	v_add_f32_e32 v84, 1.0, v65
	v_add_f32_e32 v70, 1.0, v70
	v_add_f32_e32 v85, 1.0, v66
	v_add_f32_e32 v71, 1.0, v71
	v_add_f32_e32 v86, 1.0, v67
	v_rcp_f32_e32 v64, v68
	v_rcp_f32_e32 v66, v83
	v_rcp_f32_e32 v65, v69
	v_rcp_f32_e32 v67, v84
	v_rcp_f32_e32 v68, v70
	v_rcp_f32_e32 v70, v85
	v_rcp_f32_e32 v69, v71
	v_rcp_f32_e32 v71, v86
	v_mul_f32_e32 v82, v82, v82
	v_pk_mul_f32 v[64:65], v[82:83], v[64:65] op_sel_hi:[0,1]
	v_pk_mul_f32 v[66:67], v[82:83], v[66:67] op_sel_hi:[0,1]
	v_pk_mul_f32 v[68:69], v[82:83], v[68:69] op_sel_hi:[0,1]
	v_pk_mul_f32 v[70:71], v[82:83], v[70:71] op_sel_hi:[0,1]
	v_pk_mul_f32 v[64:65], v[76:77], v[64:65]
	v_pk_mul_f32 v[66:67], v[72:73], v[66:67]
	v_pk_mul_f32 v[68:69], v[78:79], v[68:69]
	v_pk_mul_f32 v[70:71], v[74:75], v[70:71]
	v_cvt_pk_bf16_f32 v64, v64, v65
	v_cvt_pk_bf16_f32 v65, v68, v69
	v_cvt_pk_bf16_f32 v66, v66, v67
	v_cvt_pk_bf16_f32 v67, v70, v71
	global_store_dwordx4 v[80:81], v[64:67], off nt
	s_nop 1
	v_ffbh_u32_e32 v66, v177
	v_min_u32_e32 v66, 32, v66
	v_lshlrev_b64 v[64:65], v66, v[176:177]
	v_min_u32_e32 v64, 1, v64
	v_or_b32_e32 v64, v65, v64
	v_cvt_f32_u32_e32 v64, v64
	v_sub_u32_e32 v66, 32, v66
	v_add_u32_e32 v65, 0x80, v144
	v_ldexp_f32 v64, v64, v66
	v_mul_f32_e32 v64, 0x33800000, v64
	v_fmamk_f32 v64, v64, 0x3a000000, v154
	v_rsq_f32_e32 v66, v64
	v_mad_i64_i32 v[64:65], s[62:63], v65, s72, v[120:121]
	v_lshl_add_u64 v[64:65], v[64:65], 0, v[122:123]
	v_mul_f32_e32 v67, 0xbfb8aa3b, v66
	v_mul_f32_e32 v52, v52, v67
	v_mul_f32_e32 v48, v48, v67
; __device__ __forceinline__ u32x4 pack8(const f32x4 a, const f32x4 b) { u32x4 w; w.x = cvt_pk_bf16(a[0], a[1]); w.y = cvt_pk_bf16(a[2], a[3]); w.z = cvt_pk_bf16(b[0], b[1]); w.w = cvt_pk_bf16(b[2], b[3]); return w; }
; __device__ __forceinline__ float rstd_of(ssq_t ss, float inv_n) { return __builtin_amdgcn_rsqf((float)ss * (1.0f / 16777216.0f) * inv_n + 1e-6f); }
; __device__ __forceinline__ float silu_mul2(float g, float u, float c1, float c2) { return (g * u) * (c2 * __builtin_amdgcn_rcpf(1.0f + __builtin_amdgcn_exp2f(g * c1))); }
;     __device__ __forceinline__ void operator()(const f32x4 (&acc)[2][2][4][2], const Unit& u, int wr, int wc, int fr, int fq) const {
;     ...
;             for (int m = 0; m < 4; ++m) { const int row = row0 + ai * HALF + m * 16; const float rs = rstd_of(ss[row], 1.0f / 2048.0f);
;                 const float c1 = -1.4426950408889634f * rs, c2 = rs * rs;
;                 f32x4 a0, a1;
; #pragma unroll
;                 for (int e = 0; e < 4; ++e) { a0[e] = silu_mul2(acc[ai][0][m][0][e], acc[ai][1][m][0][e], c1, c2); a1[e] = silu_mul2(acc[ai][0][m][1][e], acc[ai][1][m][1][e], c1, c2); }
;                 *(u32x4*)(H + (size_t)row * 5632 + col0) = pack8(a0, a1); }
	v_mul_f32_e32 v53, v53, v67
	v_mul_f32_e32 v49, v49, v67
	v_mul_f32_e32 v54, v54, v67
	v_mul_f32_e32 v50, v50, v67
	v_mul_f32_e32 v55, v55, v67
	v_mul_f32_e32 v51, v51, v67
	v_exp_f32_e32 v52, v52
	v_exp_f32_e32 v48, v48
	v_exp_f32_e32 v53, v53
	v_exp_f32_e32 v49, v49
	v_exp_f32_e32 v54, v54
	v_exp_f32_e32 v50, v50
	v_exp_f32_e32 v55, v55
	v_exp_f32_e32 v51, v51
	v_add_f32_e32 v52, 1.0, v52
	v_add_f32_e32 v67, 1.0, v48
	v_add_f32_e32 v53, 1.0, v53
	v_add_f32_e32 v68, 1.0, v49
	v_add_f32_e32 v54, 1.0, v54
	v_add_f32_e32 v69, 1.0, v50
	v_add_f32_e32 v55, 1.0, v55
	v_add_f32_e32 v70, 1.0, v51
	v_rcp_f32_e32 v48, v52
	v_rcp_f32_e32 v50, v67
	v_rcp_f32_e32 v49, v53
	v_rcp_f32_e32 v51, v68
	v_rcp_f32_e32 v52, v54
	v_rcp_f32_e32 v54, v69
	v_rcp_f32_e32 v53, v55
	v_rcp_f32_e32 v55, v70
	v_mul_f32_e32 v66, v66, v66
	v_pk_mul_f32 v[48:49], v[66:67], v[48:49] op_sel_hi:[0,1]
	v_pk_mul_f32 v[50:51], v[66:67], v[50:51] op_sel_hi:[0,1]
	v_pk_mul_f32 v[52:53], v[66:67], v[52:53] op_sel_hi:[0,1]
	v_pk_mul_f32 v[54:55], v[66:67], v[54:55] op_sel_hi:[0,1]
	v_pk_mul_f32 v[48:49], v[60:61], v[48:49]
	v_pk_mul_f32 v[50:51], v[56:57], v[50:51]
	v_pk_mul_f32 v[52:53], v[62:63], v[52:53]
	v_pk_mul_f32 v[54:55], v[58:59], v[54:55]
	v_cvt_pk_bf16_f32 v48, v48, v49
	v_cvt_pk_bf16_f32 v49, v52, v53
	v_cvt_pk_bf16_f32 v50, v50, v51
	v_cvt_pk_bf16_f32 v51, v54, v55
	global_store_dwordx4 v[64:65], v[48:51], off nt
	s_nop 1
	v_ffbh_u32_e32 v50, v179
	v_min_u32_e32 v50, 32, v50
	v_lshlrev_b64 v[48:49], v50, v[178:179]
	v_min_u32_e32 v48, 1, v48
	v_or_b32_e32 v48, v49, v48
	v_cvt_f32_u32_e32 v48, v48
	v_sub_u32_e32 v50, 32, v50
	v_add_u32_e32 v49, 0x90, v144
	v_ldexp_f32 v48, v48, v50
	v_mul_f32_e32 v48, 0x33800000, v48
	v_fmamk_f32 v48, v48, 0x3a000000, v154
	v_rsq_f32_e32 v50, v48
	v_mad_i64_i32 v[48:49], s[62:63], v49, s72, v[120:121]
	v_lshl_add_u64 v[48:49], v[48:49], 0, v[122:123]
	v_mul_f32_e32 v51, 0xbfb8aa3b, v50
	v_mul_f32_e32 v36, v36, v51
	v_mul_f32_e32 v32, v32, v51
	v_mul_f32_e32 v37, v37, v51
	v_mul_f32_e32 v33, v33, v51
	v_mul_f32_e32 v38, v38, v51
	v_mul_f32_e32 v34, v34, v51
	v_mul_f32_e32 v39, v39, v51
	v_mul_f32_e32 v35, v35, v51
	v_exp_f32_e32 v36, v36
	v_exp_f32_e32 v32, v32
	v_exp_f32_e32 v37, v37
	v_exp_f32_e32 v33, v33
	v_exp_f32_e32 v38, v38
	v_exp_f32_e32 v34, v34
	v_exp_f32_e32 v39, v39
	v_exp_f32_e32 v35, v35
	v_add_f32_e32 v36, 1.0, v36
	v_add_f32_e32 v51, 1.0, v32
	v_add_f32_e32 v37, 1.0, v37
	v_add_f32_e32 v52, 1.0, v33
	v_add_f32_e32 v38, 1.0, v38
	v_add_f32_e32 v53, 1.0, v34
	v_add_f32_e32 v39, 1.0, v39
	v_add_f32_e32 v54, 1.0, v35
	v_rcp_f32_e32 v32, v36
	v_rcp_f32_e32 v34, v51
	v_rcp_f32_e32 v33, v37
	v_rcp_f32_e32 v35, v52
	v_rcp_f32_e32 v36, v38
	v_rcp_f32_e32 v38, v53
	v_rcp_f32_e32 v37, v39
	v_rcp_f32_e32 v39, v54
	v_mul_f32_e32 v50, v50, v50
	v_pk_mul_f32 v[32:33], v[50:51], v[32:33] op_sel_hi:[0,1]
	v_pk_mul_f32 v[34:35], v[50:51], v[34:35] op_sel_hi:[0,1]
	v_pk_mul_f32 v[36:37], v[50:51], v[36:37] op_sel_hi:[0,1]
	v_pk_mul_f32 v[38:39], v[50:51], v[38:39] op_sel_hi:[0,1]
	v_pk_mul_f32 v[32:33], v[44:45], v[32:33]
	v_pk_mul_f32 v[34:35], v[40:41], v[34:35]
	v_pk_mul_f32 v[36:37], v[46:47], v[36:37]
	v_pk_mul_f32 v[38:39], v[42:43], v[38:39]
	v_cvt_pk_bf16_f32 v32, v32, v33
	v_cvt_pk_bf16_f32 v33, v36, v37
	v_cvt_pk_bf16_f32 v34, v34, v35
	v_cvt_pk_bf16_f32 v35, v38, v39
	global_store_dwordx4 v[48:49], v[32:35], off nt
	s_nop 1
	v_ffbh_u32_e32 v34, v181
	v_min_u32_e32 v34, 32, v34
	v_lshlrev_b64 v[32:33], v34, v[180:181]
	v_min_u32_e32 v32, 1, v32
	v_or_b32_e32 v32, v33, v32
	v_cvt_f32_u32_e32 v32, v32
	v_sub_u32_e32 v34, 32, v34
	v_add_u32_e32 v33, 0xa0, v144
	v_ldexp_f32 v32, v32, v34
	v_mul_f32_e32 v32, 0x33800000, v32
; __device__ __forceinline__ u32x4 pack8(const f32x4 a, const f32x4 b) { u32x4 w; w.x = cvt_pk_bf16(a[0], a[1]); w.y = cvt_pk_bf16(a[2], a[3]); w.z = cvt_pk_bf16(b[0], b[1]); w.w = cvt_pk_bf16(b[2], b[3]); return w; }
; __device__ __forceinline__ float rstd_of(ssq_t ss, float inv_n) { return __builtin_amdgcn_rsqf((float)ss * (1.0f / 16777216.0f) * inv_n + 1e-6f); }
; __device__ __forceinline__ float silu_mul2(float g, float u, float c1, float c2) { return (g * u) * (c2 * __builtin_amdgcn_rcpf(1.0f + __builtin_amdgcn_exp2f(g * c1))); }
;     __device__ __forceinline__ void operator()(const f32x4 (&acc)[2][2][4][2], const Unit& u, int wr, int wc, int fr, int fq) const {
;     ...
;             for (int m = 0; m < 4; ++m) { const int row = row0 + ai * HALF + m * 16; const float rs = rstd_of(ss[row], 1.0f / 2048.0f);
;                 const float c1 = -1.4426950408889634f * rs, c2 = rs * rs;
;                 f32x4 a0, a1;
; #pragma unroll
;                 for (int e = 0; e < 4; ++e) { a0[e] = silu_mul2(acc[ai][0][m][0][e], acc[ai][1][m][0][e], c1, c2); a1[e] = silu_mul2(acc[ai][0][m][1][e], acc[ai][1][m][1][e], c1, c2); }
;                 *(u32x4*)(H + (size_t)row * 5632 + col0) = pack8(a0, a1); }
	v_fmamk_f32 v32, v32, 0x3a000000, v154
	v_rsq_f32_e32 v34, v32
	v_mad_i64_i32 v[32:33], s[62:63], v33, s72, v[120:121]
	v_lshl_add_u64 v[32:33], v[32:33], 0, v[122:123]
	v_mul_f32_e32 v35, 0xbfb8aa3b, v34
	v_mul_f32_e32 v20, v20, v35
	v_mul_f32_e32 v16, v16, v35
	v_mul_f32_e32 v21, v21, v35
	v_mul_f32_e32 v17, v17, v35
	v_mul_f32_e32 v22, v22, v35
	v_mul_f32_e32 v18, v18, v35
	v_mul_f32_e32 v23, v23, v35
	v_mul_f32_e32 v19, v19, v35
	v_exp_f32_e32 v20, v20
	v_exp_f32_e32 v16, v16
	v_exp_f32_e32 v21, v21
	v_exp_f32_e32 v17, v17
	v_exp_f32_e32 v22, v22
	v_exp_f32_e32 v18, v18
	v_exp_f32_e32 v23, v23
	v_exp_f32_e32 v19, v19
	v_add_f32_e32 v20, 1.0, v20
	v_add_f32_e32 v35, 1.0, v16
	v_add_f32_e32 v21, 1.0, v21
	v_add_f32_e32 v36, 1.0, v17
	v_add_f32_e32 v22, 1.0, v22
	v_add_f32_e32 v37, 1.0, v18
	v_add_f32_e32 v23, 1.0, v23
	v_add_f32_e32 v38, 1.0, v19
	v_rcp_f32_e32 v16, v20
	v_rcp_f32_e32 v18, v35
	v_rcp_f32_e32 v17, v21
	v_rcp_f32_e32 v19, v36
	v_rcp_f32_e32 v20, v22
	v_rcp_f32_e32 v22, v37
	v_rcp_f32_e32 v21, v23
	v_rcp_f32_e32 v23, v38
	v_mul_f32_e32 v34, v34, v34
	v_pk_mul_f32 v[16:17], v[34:35], v[16:17] op_sel_hi:[0,1]
	v_pk_mul_f32 v[18:19], v[34:35], v[18:19] op_sel_hi:[0,1]
	v_pk_mul_f32 v[20:21], v[34:35], v[20:21] op_sel_hi:[0,1]
	v_pk_mul_f32 v[22:23], v[34:35], v[22:23] op_sel_hi:[0,1]
	v_pk_mul_f32 v[16:17], v[28:29], v[16:17]
	v_pk_mul_f32 v[18:19], v[24:25], v[18:19]
	v_pk_mul_f32 v[20:21], v[30:31], v[20:21]
	v_pk_mul_f32 v[22:23], v[26:27], v[22:23]
	v_cvt_pk_bf16_f32 v16, v16, v17
	v_cvt_pk_bf16_f32 v17, v20, v21
	v_cvt_pk_bf16_f32 v18, v18, v19
	v_cvt_pk_bf16_f32 v19, v22, v23
	global_store_dwordx4 v[32:33], v[16:19], off nt
	s_nop 1
	v_ffbh_u32_e32 v18, v183
	v_min_u32_e32 v18, 32, v18
	v_lshlrev_b64 v[16:17], v18, v[182:183]
	v_min_u32_e32 v16, 1, v16
	v_or_b32_e32 v16, v17, v16
	v_cvt_f32_u32_e32 v16, v16
	v_sub_u32_e32 v18, 32, v18
	v_add_u32_e32 v17, 0xb0, v144
	v_ldexp_f32 v16, v16, v18
	v_mul_f32_e32 v16, 0x33800000, v16
	v_fmamk_f32 v16, v16, 0x3a000000, v154
	v_rsq_f32_e32 v18, v16
	v_mad_i64_i32 v[16:17], s[62:63], v17, s72, v[120:121]
	v_lshl_add_u64 v[16:17], v[16:17], 0, v[122:123]
	v_mul_f32_e32 v19, 0xbfb8aa3b, v18
	v_mul_f32_e32 v4, v4, v19
	v_mul_f32_e32 v0, v0, v19
	v_mul_f32_e32 v5, v5, v19
	v_mul_f32_e32 v1, v1, v19
	v_mul_f32_e32 v6, v6, v19
	v_mul_f32_e32 v2, v2, v19
	v_mul_f32_e32 v7, v7, v19
	v_mul_f32_e32 v3, v3, v19
	v_exp_f32_e32 v4, v4
	v_exp_f32_e32 v0, v0
	v_exp_f32_e32 v5, v5
	v_exp_f32_e32 v1, v1
	v_exp_f32_e32 v6, v6
	v_exp_f32_e32 v2, v2
	v_exp_f32_e32 v7, v7
	v_exp_f32_e32 v3, v3
	v_add_f32_e32 v4, 1.0, v4
	v_add_f32_e32 v19, 1.0, v0
	v_add_f32_e32 v5, 1.0, v5
	v_add_f32_e32 v20, 1.0, v1
	v_add_f32_e32 v6, 1.0, v6
	v_add_f32_e32 v21, 1.0, v2
	v_add_f32_e32 v7, 1.0, v7
	v_add_f32_e32 v22, 1.0, v3
	v_rcp_f32_e32 v0, v4
	v_rcp_f32_e32 v2, v19
	v_rcp_f32_e32 v1, v5
	v_rcp_f32_e32 v3, v20
	v_rcp_f32_e32 v4, v6
	v_rcp_f32_e32 v6, v21
	v_rcp_f32_e32 v5, v7
	v_rcp_f32_e32 v7, v22
	v_mul_f32_e32 v18, v18, v18
	v_pk_mul_f32 v[0:1], v[18:19], v[0:1] op_sel_hi:[0,1]
	v_pk_mul_f32 v[2:3], v[18:19], v[2:3] op_sel_hi:[0,1]
	v_pk_mul_f32 v[4:5], v[18:19], v[4:5] op_sel_hi:[0,1]
	v_pk_mul_f32 v[6:7], v[18:19], v[6:7] op_sel_hi:[0,1]
	v_pk_mul_f32 v[0:1], v[12:13], v[0:1]
	v_pk_mul_f32 v[2:3], v[8:9], v[2:3]
	v_pk_mul_f32 v[4:5], v[14:15], v[4:5]
	v_pk_mul_f32 v[6:7], v[10:11], v[6:7]
	v_cvt_pk_bf16_f32 v0, v0, v1
	v_cvt_pk_bf16_f32 v1, v4, v5
	v_cvt_pk_bf16_f32 v2, v2, v3
	v_cvt_pk_bf16_f32 v3, v6, v7
	global_store_dwordx4 v[16:17], v[0:3], off nt
	s_cbranch_vccnz .LBB0_1386
	s_andn2_b64 vcc, exec, s[0:1]
	s_cbranch_vccnz .LBB0_1385
	s_barrier
	s_branch .LBB0_1385

; __device__ __forceinline__ u32x4 pack8(const f32x4 a, const f32x4 b) { u32x4 w; w.x = cvt_pk_bf16(a[0], a[1]); w.y = cvt_pk_bf16(a[2], a[3]); w.z = cvt_pk_bf16(b[0], b[1]); w.w = cvt_pk_bf16(b[2], b[3]); return w; }
; __device__ __forceinline__ float rstd_of(ssq_t ss, float inv_n) { return __builtin_amdgcn_rsqf((float)ss * (1.0f / 16777216.0f) * inv_n + 1e-6f); }
; __device__ __forceinline__ float silu_mul2(float g, float u, float c1, float c2) { return (g * u) * (c2 * __builtin_amdgcn_rcpf(1.0f + __builtin_amdgcn_exp2f(g * c1))); }
;     __device__ __forceinline__ void operator()(const f32x4 (&acc)[2][2][4][2], const Unit& u, int wr, int wc, int fr, int fq) const {
;     ...
;             for (int m = 0; m < 4; ++m) { const int row = row0 + ai * HALF + m * 16; const float rs = rstd_of(ss[row], 1.0f / 2048.0f);
;                 const float c1 = -1.4426950408889634f * rs, c2 = rs * rs;
;                 f32x4 a0, a1;
; #pragma unroll
;                 for (int e = 0; e < 4; ++e) { a0[e] = silu_mul2(acc[ai][0][m][0][e], acc[ai][1][m][0][e], c1, c2); a1[e] = silu_mul2(acc[ai][0][m][1][e], acc[ai][1][m][1][e], c1, c2); }
;                 *(u32x4*)(H + (size_t)row * 5632 + col0) = pack8(a0, a1); }
.LBB0_2172:
	v_lshl_add_u32 v144, s22, 8, v148
	v_ashrrev_i32_e32 v145, 31, v144
	v_lshl_add_u64 v[146:147], v[144:145], 3, s[4:5]
	global_load_dwordx2 v[156:157], v[146:147], off
	global_load_dwordx2 v[170:171], v[146:147], off offset:128
	global_load_dwordx2 v[172:173], v[146:147], off offset:256
	global_load_dwordx2 v[174:175], v[146:147], off offset:384
	global_load_dwordx2 v[176:177], v[146:147], off offset:1024
	global_load_dwordx2 v[178:179], v[146:147], off offset:1152
	global_load_dwordx2 v[180:181], v[146:147], off offset:1280
	global_load_dwordx2 v[182:183], v[146:147], off offset:1408
	v_pk_mul_f32 v[160:161], v[114:115], v[122:123]
	v_pk_mul_f32 v[126:127], v[118:119], v[126:127]
	v_pk_mul_f32 v[124:125], v[116:117], v[124:125]
	v_pk_mul_f32 v[162:163], v[112:113], v[120:121]
	v_lshl_add_u32 v158, s53, 7, v150
	v_mov_b64_e32 v[120:121], s[44:45]
	v_ashrrev_i32_e32 v159, 31, v158
	v_mad_i64_i32 v[164:165], s[24:25], v144, s52, v[120:121]
	v_pk_mul_f32 v[110:111], v[102:103], v[110:111]
	v_pk_mul_f32 v[108:109], v[100:101], v[108:109]
	v_pk_mul_f32 v[106:107], v[98:99], v[106:107]
	v_pk_mul_f32 v[104:105], v[96:97], v[104:105]
	v_pk_mul_f32 v[94:95], v[86:87], v[94:95]
	v_pk_mul_f32 v[92:93], v[84:85], v[92:93]
	v_pk_mul_f32 v[90:91], v[82:83], v[90:91]
	v_pk_mul_f32 v[88:89], v[80:81], v[88:89]
	v_pk_mul_f32 v[78:79], v[70:71], v[78:79]
	v_pk_mul_f32 v[76:77], v[68:69], v[76:77]
	v_pk_mul_f32 v[74:75], v[66:67], v[74:75]
	v_pk_mul_f32 v[72:73], v[64:65], v[72:73]
	v_pk_mul_f32 v[62:63], v[54:55], v[62:63]
	v_pk_mul_f32 v[60:61], v[52:53], v[60:61]
	v_pk_mul_f32 v[58:59], v[50:51], v[58:59]
	v_pk_mul_f32 v[56:57], v[48:49], v[56:57]
	v_pk_mul_f32 v[46:47], v[38:39], v[46:47]
	v_pk_mul_f32 v[44:45], v[36:37], v[44:45]
	v_pk_mul_f32 v[42:43], v[34:35], v[42:43]
	v_pk_mul_f32 v[40:41], v[32:33], v[40:41]
	v_pk_mul_f32 v[30:31], v[22:23], v[30:31]
	v_pk_mul_f32 v[28:29], v[20:21], v[28:29]
	v_pk_mul_f32 v[26:27], v[18:19], v[26:27]
	v_pk_mul_f32 v[24:25], v[16:17], v[24:25]
	v_pk_mul_f32 v[14:15], v[6:7], v[14:15]
	v_pk_mul_f32 v[12:13], v[4:5], v[12:13]
	v_pk_mul_f32 v[10:11], v[2:3], v[10:11]
	v_pk_mul_f32 v[8:9], v[0:1], v[8:9]
	s_andn2_b64 vcc, exec, s[2:3]
	s_mov_b64 s[2:3], -1
	s_waitcnt vmcnt(0)
	v_ffbh_u32_e32 v122, v157
	v_min_u32_e32 v145, 32, v122
	v_lshlrev_b64 v[122:123], v145, v[156:157]
	v_min_u32_e32 v122, 1, v122
	v_or_b32_e32 v122, v123, v122
	v_cvt_f32_u32_e32 v155, v122
	v_sub_u32_e32 v145, 32, v145
	v_or_b32_e32 v156, 16, v144
	v_lshlrev_b64 v[122:123], 1, v[158:159]
	v_ldexp_f32 v145, v155, v145
	v_mul_f32_e32 v145, 0x33800000, v145
	v_fmamk_f32 v145, v145, 0x3a000000, v154
	v_rsq_f32_e32 v145, v145
	v_ashrrev_i32_e32 v157, 31, v156
	v_lshl_add_u64 v[158:159], v[164:165], 0, v[122:123]
	v_lshl_add_u64 v[164:165], v[156:157], 3, s[4:5]
	v_mul_f32_e32 v155, 0xbfb8aa3b, v145
	v_mul_f32_e32 v116, v116, v155
	v_mul_f32_e32 v112, v112, v155
	v_mul_f32_e32 v117, v117, v155
	v_mul_f32_e32 v113, v113, v155
	v_mul_f32_e32 v118, v118, v155
	v_mul_f32_e32 v114, v114, v155
	v_mul_f32_e32 v119, v119, v155
	v_mul_f32_e32 v115, v115, v155
	v_exp_f32_e32 v116, v116
	v_exp_f32_e32 v112, v112
	v_exp_f32_e32 v117, v117
	v_exp_f32_e32 v113, v113
	v_exp_f32_e32 v118, v118
	v_exp_f32_e32 v114, v114
	v_exp_f32_e32 v119, v119
	v_exp_f32_e32 v115, v115
	v_mul_f32_e32 v166, v145, v145
	v_add_f32_e32 v116, 1.0, v116
	v_add_f32_e32 v145, 1.0, v112
	v_add_f32_e32 v117, 1.0, v117
	v_add_f32_e32 v155, 1.0, v113
	v_add_f32_e32 v118, 1.0, v118
	v_add_f32_e32 v157, 1.0, v114
	v_add_f32_e32 v119, 1.0, v119
	v_add_f32_e32 v167, 1.0, v115
	v_rcp_f32_e32 v112, v116
	v_rcp_f32_e32 v114, v145
	v_rcp_f32_e32 v113, v117
	v_rcp_f32_e32 v115, v155
	v_rcp_f32_e32 v116, v118
	v_rcp_f32_e32 v118, v157
	v_rcp_f32_e32 v117, v119
	v_rcp_f32_e32 v119, v167
	v_pk_mul_f32 v[112:113], v[166:167], v[112:113] op_sel_hi:[0,1]
	v_pk_mul_f32 v[114:115], v[166:167], v[114:115] op_sel_hi:[0,1]
	v_pk_mul_f32 v[116:117], v[166:167], v[116:117] op_sel_hi:[0,1]
	v_pk_mul_f32 v[118:119], v[166:167], v[118:119] op_sel_hi:[0,1]
	v_pk_mul_f32 v[112:113], v[124:125], v[112:113]
	v_pk_mul_f32 v[114:115], v[162:163], v[114:115]
	v_pk_mul_f32 v[116:117], v[126:127], v[116:117]
	v_pk_mul_f32 v[118:119], v[160:161], v[118:119]
	v_cvt_pk_bf16_f32 v112, v112, v113
	v_cvt_pk_bf16_f32 v113, v116, v117
	v_cvt_pk_bf16_f32 v114, v114, v115
	v_cvt_pk_bf16_f32 v115, v118, v119
	global_store_dwordx4 v[158:159], v[112:115], off nt
	s_nop 1
	s_nop 0
	v_or_b32_e32 v114, 32, v144
	v_ffbh_u32_e32 v115, v171
	v_min_u32_e32 v115, 32, v115
	v_lshlrev_b64 v[112:113], v115, v[170:171]
	v_min_u32_e32 v112, 1, v112
	v_or_b32_e32 v112, v113, v112
	v_cvt_f32_u32_e32 v116, v112
	v_sub_u32_e32 v115, 32, v115
	v_mad_i64_i32 v[112:113], s[24:25], v156, s52, v[120:121]
	v_ldexp_f32 v115, v116, v115
	v_mul_f32_e32 v115, 0x33800000, v115
	v_fmamk_f32 v115, v115, 0x3a000000, v154
	v_rsq_f32_e32 v118, v115
	v_ashrrev_i32_e32 v115, 31, v114
	v_lshl_add_u64 v[116:117], v[114:115], 3, s[4:5]
	v_lshl_add_u64 v[112:113], v[112:113], 0, v[122:123]
	v_mul_f32_e32 v115, 0xbfb8aa3b, v118
	v_mul_f32_e32 v100, v100, v115
	v_mul_f32_e32 v96, v96, v115
	v_mul_f32_e32 v101, v101, v115
	v_mul_f32_e32 v97, v97, v115
	v_mul_f32_e32 v102, v102, v115
	v_mul_f32_e32 v98, v98, v115
	v_mul_f32_e32 v103, v103, v115
	v_mul_f32_e32 v99, v99, v115
	v_exp_f32_e32 v100, v100
	v_exp_f32_e32 v96, v96
	v_exp_f32_e32 v101, v101
	v_exp_f32_e32 v97, v97
	v_exp_f32_e32 v102, v102
	v_exp_f32_e32 v98, v98
	v_exp_f32_e32 v103, v103
	v_exp_f32_e32 v99, v99
	v_add_f32_e32 v100, 1.0, v100
	v_add_f32_e32 v115, 1.0, v96
	v_add_f32_e32 v101, 1.0, v101
; __device__ __forceinline__ u32x4 pack8(const f32x4 a, const f32x4 b) { u32x4 w; w.x = cvt_pk_bf16(a[0], a[1]); w.y = cvt_pk_bf16(a[2], a[3]); w.z = cvt_pk_bf16(b[0], b[1]); w.w = cvt_pk_bf16(b[2], b[3]); return w; }
; __device__ __forceinline__ float rstd_of(ssq_t ss, float inv_n) { return __builtin_amdgcn_rsqf((float)ss * (1.0f / 16777216.0f) * inv_n + 1e-6f); }
; __device__ __forceinline__ void ss_add(ssq_t* p, float sq) { __hip_atomic_fetch_add(p, (ssq_t)(sq * 16777216.0f), __ATOMIC_RELAXED, __HIP_MEMORY_SCOPE_AGENT); }
; __device__ __forceinline__ float silu_mul(float g, float u) { return g * u * __builtin_amdgcn_rcpf(1.0f + __builtin_amdgcn_exp2f(-1.4426950408889634f * g)); }
; __device__ __forceinline__ float silu_mul2(float g, float u, float c1, float c2) { return (g * u) * (c2 * __builtin_amdgcn_rcpf(1.0f + __builtin_amdgcn_exp2f(g * c1))); }
; __device__ __forceinline__ float dot4(const f32x4 a) { return (a[0] * a[0] + a[1] * a[1]) + (a[2] * a[2] + a[3] * a[3]); }
;     __device__ __forceinline__ void operator()(const f32x4 (&acc)[2][2][4][2], const Unit& u, int wr, int wc, int fr, int fq) const {
;         const int row0 = u.pm * BM + wr * 64 + fr, col0 = u.pn * 128 + wc * 32 + 8 * fq;
; #pragma unroll
;         for (int ai = 0; ai < 2; ++ai)
; #pragma unroll
;             for (int m = 0; m < 4; ++m) { const int row = row0 + ai * HALF + m * 16; const float rs = rstd_of(ss[row], 1.0f / 2048.0f);
;                 const float c1 = -1.4426950408889634f * rs, c2 = rs * rs;
;                 f32x4 a0, a1;
; #pragma unroll
;                 for (int e = 0; e < 4; ++e) { a0[e] = silu_mul2(acc[ai][0][m][0][e], acc[ai][1][m][0][e], c1, c2); a1[e] = silu_mul2(acc[ai][0][m][1][e], acc[ai][1][m][1][e], c1, c2); }
;                 *(u32x4*)(H + (size_t)row * 5632 + col0) = pack8(a0, a1); }
	v_add_f32_e32 v119, 1.0, v97
	v_add_f32_e32 v102, 1.0, v102
	v_add_f32_e32 v124, 1.0, v98
	v_add_f32_e32 v103, 1.0, v103
	v_add_f32_e32 v125, 1.0, v99
	v_rcp_f32_e32 v96, v100
	v_rcp_f32_e32 v98, v115
	v_rcp_f32_e32 v97, v101
	v_rcp_f32_e32 v99, v119
	v_rcp_f32_e32 v100, v102
	v_rcp_f32_e32 v102, v124
	v_rcp_f32_e32 v101, v103
	v_rcp_f32_e32 v103, v125
	v_mul_f32_e32 v118, v118, v118
	v_pk_mul_f32 v[96:97], v[118:119], v[96:97] op_sel_hi:[0,1]
	v_pk_mul_f32 v[98:99], v[118:119], v[98:99] op_sel_hi:[0,1]
	v_pk_mul_f32 v[100:101], v[118:119], v[100:101] op_sel_hi:[0,1]
	v_pk_mul_f32 v[102:103], v[118:119], v[102:103] op_sel_hi:[0,1]
	v_pk_mul_f32 v[96:97], v[108:109], v[96:97]
	v_pk_mul_f32 v[98:99], v[104:105], v[98:99]
	v_pk_mul_f32 v[100:101], v[110:111], v[100:101]
	v_pk_mul_f32 v[102:103], v[106:107], v[102:103]
	v_cvt_pk_bf16_f32 v96, v96, v97
	v_cvt_pk_bf16_f32 v97, v100, v101
	v_cvt_pk_bf16_f32 v98, v98, v99
	v_cvt_pk_bf16_f32 v99, v102, v103
	global_store_dwordx4 v[112:113], v[96:99], off nt
	s_nop 1
	s_nop 0
	v_or_b32_e32 v98, 48, v144
	v_ffbh_u32_e32 v99, v173
	v_min_u32_e32 v99, 32, v99
	v_lshlrev_b64 v[96:97], v99, v[172:173]
	v_min_u32_e32 v96, 1, v96
	v_or_b32_e32 v96, v97, v96
	v_cvt_f32_u32_e32 v100, v96
	v_sub_u32_e32 v99, 32, v99
	v_mad_i64_i32 v[96:97], s[24:25], v114, s52, v[120:121]
	v_ldexp_f32 v99, v100, v99
	v_mul_f32_e32 v99, 0x33800000, v99
	v_fmamk_f32 v99, v99, 0x3a000000, v154
	v_rsq_f32_e32 v102, v99
	v_ashrrev_i32_e32 v99, 31, v98
	v_lshl_add_u64 v[100:101], v[98:99], 3, s[4:5]
	v_lshl_add_u64 v[96:97], v[96:97], 0, v[122:123]
	v_mul_f32_e32 v99, 0xbfb8aa3b, v102
	v_mul_f32_e32 v84, v84, v99
	v_mul_f32_e32 v80, v80, v99
	v_mul_f32_e32 v85, v85, v99
	v_mul_f32_e32 v81, v81, v99
	v_mul_f32_e32 v86, v86, v99
	v_mul_f32_e32 v82, v82, v99
	v_mul_f32_e32 v87, v87, v99
	v_mul_f32_e32 v83, v83, v99
	v_exp_f32_e32 v84, v84
	v_exp_f32_e32 v80, v80
	v_exp_f32_e32 v85, v85
	v_exp_f32_e32 v81, v81
	v_exp_f32_e32 v86, v86
	v_exp_f32_e32 v82, v82
	v_exp_f32_e32 v87, v87
	v_exp_f32_e32 v83, v83
	v_add_f32_e32 v84, 1.0, v84
	v_add_f32_e32 v99, 1.0, v80
	v_add_f32_e32 v85, 1.0, v85
	v_add_f32_e32 v103, 1.0, v81
	v_add_f32_e32 v86, 1.0, v86
	v_add_f32_e32 v104, 1.0, v82
	v_add_f32_e32 v87, 1.0, v87
	v_add_f32_e32 v105, 1.0, v83
	v_rcp_f32_e32 v80, v84
	v_rcp_f32_e32 v82, v99
	v_rcp_f32_e32 v81, v85
	v_rcp_f32_e32 v83, v103
	v_rcp_f32_e32 v84, v86
	v_rcp_f32_e32 v86, v104
	v_rcp_f32_e32 v85, v87
	v_rcp_f32_e32 v87, v105
	v_mul_f32_e32 v102, v102, v102
	v_pk_mul_f32 v[80:81], v[102:103], v[80:81] op_sel_hi:[0,1]
	v_pk_mul_f32 v[82:83], v[102:103], v[82:83] op_sel_hi:[0,1]
	v_pk_mul_f32 v[84:85], v[102:103], v[84:85] op_sel_hi:[0,1]
	v_pk_mul_f32 v[86:87], v[102:103], v[86:87] op_sel_hi:[0,1]
	v_pk_mul_f32 v[80:81], v[92:93], v[80:81]
	v_pk_mul_f32 v[82:83], v[88:89], v[82:83]
	v_pk_mul_f32 v[84:85], v[94:95], v[84:85]
	v_pk_mul_f32 v[86:87], v[90:91], v[86:87]
	v_cvt_pk_bf16_f32 v80, v80, v81
	v_cvt_pk_bf16_f32 v81, v84, v85
	v_cvt_pk_bf16_f32 v82, v82, v83
	v_cvt_pk_bf16_f32 v83, v86, v87
	global_store_dwordx4 v[96:97], v[80:83], off nt
	s_nop 1
	v_ffbh_u32_e32 v82, v175
	v_min_u32_e32 v82, 32, v82
	v_lshlrev_b64 v[80:81], v82, v[174:175]
	v_min_u32_e32 v80, 1, v80
	v_or_b32_e32 v80, v81, v80
	v_cvt_f32_u32_e32 v80, v80
	v_sub_u32_e32 v81, 32, v82
	v_ldexp_f32 v80, v80, v81
	v_mul_f32_e32 v80, 0x33800000, v80
	v_fmamk_f32 v80, v80, 0x3a000000, v154
	v_rsq_f32_e32 v82, v80
	v_mad_i64_i32 v[80:81], s[24:25], v98, s52, v[120:121]
	v_lshl_add_u64 v[80:81], v[80:81], 0, v[122:123]
	v_mul_f32_e32 v83, 0xbfb8aa3b, v82
	v_mul_f32_e32 v68, v68, v83
	v_mul_f32_e32 v64, v64, v83
	v_mul_f32_e32 v69, v69, v83
	v_mul_f32_e32 v65, v65, v83
	v_mul_f32_e32 v70, v70, v83
	v_mul_f32_e32 v66, v66, v83
	v_mul_f32_e32 v71, v71, v83
	v_mul_f32_e32 v67, v67, v83
	v_exp_f32_e32 v68, v68
	v_exp_f32_e32 v64, v64
	v_exp_f32_e32 v69, v69
	v_exp_f32_e32 v65, v65
	v_exp_f32_e32 v70, v70
	v_exp_f32_e32 v66, v66
	v_exp_f32_e32 v71, v71
	v_exp_f32_e32 v67, v67
	v_add_f32_e32 v68, 1.0, v68
	v_add_f32_e32 v83, 1.0, v64
	v_add_f32_e32 v69, 1.0, v69
	v_add_f32_e32 v84, 1.0, v65
	v_add_f32_e32 v70, 1.0, v70
	v_add_f32_e32 v85, 1.0, v66
	v_add_f32_e32 v71, 1.0, v71
	v_add_f32_e32 v86, 1.0, v67
	v_rcp_f32_e32 v64, v68
	v_rcp_f32_e32 v66, v83
	v_rcp_f32_e32 v65, v69
	v_rcp_f32_e32 v67, v84
	v_rcp_f32_e32 v68, v70
	v_rcp_f32_e32 v70, v85
	v_rcp_f32_e32 v69, v71
	v_rcp_f32_e32 v71, v86
	v_mul_f32_e32 v82, v82, v82
	v_pk_mul_f32 v[64:65], v[82:83], v[64:65] op_sel_hi:[0,1]
	v_pk_mul_f32 v[66:67], v[82:83], v[66:67] op_sel_hi:[0,1]
	v_pk_mul_f32 v[68:69], v[82:83], v[68:69] op_sel_hi:[0,1]
	v_pk_mul_f32 v[70:71], v[82:83], v[70:71] op_sel_hi:[0,1]
	v_pk_mul_f32 v[64:65], v[76:77], v[64:65]
	v_pk_mul_f32 v[66:67], v[72:73], v[66:67]
	v_pk_mul_f32 v[68:69], v[78:79], v[68:69]
	v_pk_mul_f32 v[70:71], v[74:75], v[70:71]
	v_cvt_pk_bf16_f32 v64, v64, v65
	v_cvt_pk_bf16_f32 v65, v68, v69
	v_cvt_pk_bf16_f32 v66, v66, v67
	v_cvt_pk_bf16_f32 v67, v70, v71
	global_store_dwordx4 v[80:81], v[64:67], off nt
	s_nop 1
	v_ffbh_u32_e32 v66, v177
	v_min_u32_e32 v66, 32, v66
	v_lshlrev_b64 v[64:65], v66, v[176:177]
	v_min_u32_e32 v64, 1, v64
	v_or_b32_e32 v64, v65, v64
	v_cvt_f32_u32_e32 v64, v64
	v_sub_u32_e32 v66, 32, v66
	v_add_u32_e32 v65, 0x80, v144
	v_ldexp_f32 v64, v64, v66
	v_mul_f32_e32 v64, 0x33800000, v64
	v_fmamk_f32 v64, v64, 0x3a000000, v154
	v_rsq_f32_e32 v66, v64
	v_mad_i64_i32 v[64:65], s[24:25], v65, s52, v[120:121]
	v_lshl_add_u64 v[64:65], v[64:65], 0, v[122:123]
	v_mul_f32_e32 v67, 0xbfb8aa3b, v66
	v_mul_f32_e32 v52, v52, v67
	v_mul_f32_e32 v48, v48, v67
; __device__ __forceinline__ u32x4 pack8(const f32x4 a, const f32x4 b) { u32x4 w; w.x = cvt_pk_bf16(a[0], a[1]); w.y = cvt_pk_bf16(a[2], a[3]); w.z = cvt_pk_bf16(b[0], b[1]); w.w = cvt_pk_bf16(b[2], b[3]); return w; }
; __device__ __forceinline__ float rstd_of(ssq_t ss, float inv_n) { return __builtin_amdgcn_rsqf((float)ss * (1.0f / 16777216.0f) * inv_n + 1e-6f); }
; __device__ __forceinline__ void ss_add(ssq_t* p, float sq) { __hip_atomic_fetch_add(p, (ssq_t)(sq * 16777216.0f), __ATOMIC_RELAXED, __HIP_MEMORY_SCOPE_AGENT); }
; __device__ __forceinline__ float silu_mul(float g, float u) { return g * u * __builtin_amdgcn_rcpf(1.0f + __builtin_amdgcn_exp2f(-1.4426950408889634f * g)); }
; __device__ __forceinline__ float silu_mul2(float g, float u, float c1, float c2) { return (g * u) * (c2 * __builtin_amdgcn_rcpf(1.0f + __builtin_amdgcn_exp2f(g * c1))); }
; __device__ __forceinline__ float dot4(const f32x4 a) { return (a[0] * a[0] + a[1] * a[1]) + (a[2] * a[2] + a[3] * a[3]); }
;     __device__ __forceinline__ void operator()(const f32x4 (&acc)[2][2][4][2], const Unit& u, int wr, int wc, int fr, int fq) const {
;         const int row0 = u.pm * BM + wr * 64 + fr, col0 = u.pn * 128 + wc * 32 + 8 * fq;
; #pragma unroll
;         for (int ai = 0; ai < 2; ++ai)
; #pragma unroll
;             for (int m = 0; m < 4; ++m) { const int row = row0 + ai * HALF + m * 16; const float rs = rstd_of(ss[row], 1.0f / 2048.0f);
;                 const float c1 = -1.4426950408889634f * rs, c2 = rs * rs;
;                 f32x4 a0, a1;
; #pragma unroll
;                 for (int e = 0; e < 4; ++e) { a0[e] = silu_mul2(acc[ai][0][m][0][e], acc[ai][1][m][0][e], c1, c2); a1[e] = silu_mul2(acc[ai][0][m][1][e], acc[ai][1][m][1][e], c1, c2); }
;                 *(u32x4*)(H + (size_t)row * 5632 + col0) = pack8(a0, a1); }
	v_mul_f32_e32 v53, v53, v67
	v_mul_f32_e32 v49, v49, v67
	v_mul_f32_e32 v54, v54, v67
	v_mul_f32_e32 v50, v50, v67
	v_mul_f32_e32 v55, v55, v67
	v_mul_f32_e32 v51, v51, v67
	v_exp_f32_e32 v52, v52
	v_exp_f32_e32 v48, v48
	v_exp_f32_e32 v53, v53
	v_exp_f32_e32 v49, v49
	v_exp_f32_e32 v54, v54
	v_exp_f32_e32 v50, v50
	v_exp_f32_e32 v55, v55
	v_exp_f32_e32 v51, v51
	v_add_f32_e32 v52, 1.0, v52
	v_add_f32_e32 v67, 1.0, v48
	v_add_f32_e32 v53, 1.0, v53
	v_add_f32_e32 v68, 1.0, v49
	v_add_f32_e32 v54, 1.0, v54
	v_add_f32_e32 v69, 1.0, v50
	v_add_f32_e32 v55, 1.0, v55
	v_add_f32_e32 v70, 1.0, v51
	v_rcp_f32_e32 v48, v52
	v_rcp_f32_e32 v50, v67
	v_rcp_f32_e32 v49, v53
	v_rcp_f32_e32 v51, v68
	v_rcp_f32_e32 v52, v54
	v_rcp_f32_e32 v54, v69
	v_rcp_f32_e32 v53, v55
	v_rcp_f32_e32 v55, v70
	v_mul_f32_e32 v66, v66, v66
	v_pk_mul_f32 v[48:49], v[66:67], v[48:49] op_sel_hi:[0,1]
	v_pk_mul_f32 v[50:51], v[66:67], v[50:51] op_sel_hi:[0,1]
	v_pk_mul_f32 v[52:53], v[66:67], v[52:53] op_sel_hi:[0,1]
	v_pk_mul_f32 v[54:55], v[66:67], v[54:55] op_sel_hi:[0,1]
	v_pk_mul_f32 v[48:49], v[60:61], v[48:49]
	v_pk_mul_f32 v[50:51], v[56:57], v[50:51]
	v_pk_mul_f32 v[52:53], v[62:63], v[52:53]
	v_pk_mul_f32 v[54:55], v[58:59], v[54:55]
	v_cvt_pk_bf16_f32 v48, v48, v49
	v_cvt_pk_bf16_f32 v49, v52, v53
	v_cvt_pk_bf16_f32 v50, v50, v51
	v_cvt_pk_bf16_f32 v51, v54, v55
	global_store_dwordx4 v[64:65], v[48:51], off nt
	s_nop 1
	v_ffbh_u32_e32 v50, v179
	v_min_u32_e32 v50, 32, v50
	v_lshlrev_b64 v[48:49], v50, v[178:179]
	v_min_u32_e32 v48, 1, v48
	v_or_b32_e32 v48, v49, v48
	v_cvt_f32_u32_e32 v48, v48
	v_sub_u32_e32 v50, 32, v50
	v_add_u32_e32 v49, 0x90, v144
	v_ldexp_f32 v48, v48, v50
	v_mul_f32_e32 v48, 0x33800000, v48
	v_fmamk_f32 v48, v48, 0x3a000000, v154
	v_rsq_f32_e32 v50, v48
	v_mad_i64_i32 v[48:49], s[24:25], v49, s52, v[120:121]
	v_lshl_add_u64 v[48:49], v[48:49], 0, v[122:123]
	v_mul_f32_e32 v51, 0xbfb8aa3b, v50
	v_mul_f32_e32 v36, v36, v51
	v_mul_f32_e32 v32, v32, v51
	v_mul_f32_e32 v37, v37, v51
	v_mul_f32_e32 v33, v33, v51
	v_mul_f32_e32 v38, v38, v51
	v_mul_f32_e32 v34, v34, v51
	v_mul_f32_e32 v39, v39, v51
	v_mul_f32_e32 v35, v35, v51
	v_exp_f32_e32 v36, v36
	v_exp_f32_e32 v32, v32
	v_exp_f32_e32 v37, v37
	v_exp_f32_e32 v33, v33
	v_exp_f32_e32 v38, v38
	v_exp_f32_e32 v34, v34
	v_exp_f32_e32 v39, v39
	v_exp_f32_e32 v35, v35
	v_add_f32_e32 v36, 1.0, v36
	v_add_f32_e32 v51, 1.0, v32
	v_add_f32_e32 v37, 1.0, v37
	v_add_f32_e32 v52, 1.0, v33
	v_add_f32_e32 v38, 1.0, v38
	v_add_f32_e32 v53, 1.0, v34
	v_add_f32_e32 v39, 1.0, v39
	v_add_f32_e32 v54, 1.0, v35
	v_rcp_f32_e32 v32, v36
	v_rcp_f32_e32 v34, v51
	v_rcp_f32_e32 v33, v37
	v_rcp_f32_e32 v35, v52
	v_rcp_f32_e32 v36, v38
	v_rcp_f32_e32 v38, v53
	v_rcp_f32_e32 v37, v39
	v_rcp_f32_e32 v39, v54
	v_mul_f32_e32 v50, v50, v50
	v_pk_mul_f32 v[32:33], v[50:51], v[32:33] op_sel_hi:[0,1]
	v_pk_mul_f32 v[34:35], v[50:51], v[34:35] op_sel_hi:[0,1]
	v_pk_mul_f32 v[36:37], v[50:51], v[36:37] op_sel_hi:[0,1]
	v_pk_mul_f32 v[38:39], v[50:51], v[38:39] op_sel_hi:[0,1]
	v_pk_mul_f32 v[32:33], v[44:45], v[32:33]
	v_pk_mul_f32 v[34:35], v[40:41], v[34:35]
	v_pk_mul_f32 v[36:37], v[46:47], v[36:37]
	v_pk_mul_f32 v[38:39], v[42:43], v[38:39]
	v_cvt_pk_bf16_f32 v32, v32, v33
	v_cvt_pk_bf16_f32 v33, v36, v37
	v_cvt_pk_bf16_f32 v34, v34, v35
	v_cvt_pk_bf16_f32 v35, v38, v39
	global_store_dwordx4 v[48:49], v[32:35], off nt
	s_nop 1
	v_ffbh_u32_e32 v34, v181
	v_min_u32_e32 v34, 32, v34
	v_lshlrev_b64 v[32:33], v34, v[180:181]
	v_min_u32_e32 v32, 1, v32
	v_or_b32_e32 v32, v33, v32
	v_cvt_f32_u32_e32 v32, v32
	v_sub_u32_e32 v34, 32, v34
	v_add_u32_e32 v33, 0xa0, v144
	v_ldexp_f32 v32, v32, v34
	v_mul_f32_e32 v32, 0x33800000, v32
; __device__ __forceinline__ float rstd_of(ssq_t ss, float inv_n) { return __builtin_amdgcn_rsqf((float)ss * (1.0f / 16777216.0f) * inv_n + 1e-6f); }
; __device__ __forceinline__ void ss_add(ssq_t* p, float sq) { __hip_atomic_fetch_add(p, (ssq_t)(sq * 16777216.0f), __ATOMIC_RELAXED, __HIP_MEMORY_SCOPE_AGENT); }
; __device__ __forceinline__ float silu_mul(float g, float u) { return g * u * __builtin_amdgcn_rcpf(1.0f + __builtin_amdgcn_exp2f(-1.4426950408889634f * g)); }
; __device__ __forceinline__ float silu_mul2(float g, float u, float c1, float c2) { return (g * u) * (c2 * __builtin_amdgcn_rcpf(1.0f + __builtin_amdgcn_exp2f(g * c1))); }
; __device__ __forceinline__ float dot4(const f32x4 a) { return (a[0] * a[0] + a[1] * a[1]) + (a[2] * a[2] + a[3] * a[3]); }
;     __device__ __forceinline__ void operator()(const f32x4 (&acc)[2][2][4][2], const Unit& u, int wr, int wc, int fr, int fq) const {
;         const int row0 = u.pm * BM + wr * 64 + fr, col0 = u.pn * 128 + wc * 32 + 8 * fq;
; #pragma unroll
;         for (int ai = 0; ai < 2; ++ai)
; #pragma unroll
;             for (int m = 0; m < 4; ++m) { const int row = row0 + ai * HALF + m * 16; const float rs = rstd_of(ss[row], 1.0f / 2048.0f);
;                 const float c1 = -1.4426950408889634f * rs, c2 = rs * rs;
;                 f32x4 a0, a1;
; #pragma unroll
;                 for (int e = 0; e < 4; ++e) { a0[e] = silu_mul2(acc[ai][0][m][0][e], acc[ai][1][m][0][e], c1, c2); a1[e] = silu_mul2(acc[ai][0][m][1][e], acc[ai][1][m][1][e], c1, c2); }
;                 *(u32x4*)(H + (size_t)row * 5632 + col0) = pack8(a0, a1); }
; template <class Epi, class Sched, bool ALIGN_EPI = false, bool SP2 = false>
; __device__ __forceinline__ void gemm_phase(PG8_LAS unsigned char* lds, const Gemm g, const Sched& S, const Epi& E, const int wave_in) {
;     ...
;         if constexpr (ALIGN_EPI) { if (wr == 0) PG8_BAR; }
;         if constexpr (!Epi::AFTER_DRAIN) { E(acc, cur, wr, wc, fr, fq); S.done(cur); }
;         if (!has_next) break;
; #pragma unroll
;         for (int a = 0; a < 2; ++a)
; #pragma unroll
;             for (int b = 0; b < 2; ++b)
; #pragma unroll
;                 for (int m = 0; m < 4; ++m)
; #pragma unroll
;                     for (int n = 0; n < 2; ++n) acc[a][b][m][n] = (f32x4){0.f, 0.f, 0.f, 0.f};
;         cur = nxt; cA = nA; cB = nB; ++ui;
;         if constexpr (ALIGN_EPI) { if (wr == 1) PG8_BAR; }
	v_fmamk_f32 v32, v32, 0x3a000000, v154
	v_rsq_f32_e32 v34, v32
	v_mad_i64_i32 v[32:33], s[24:25], v33, s52, v[120:121]
	v_lshl_add_u64 v[32:33], v[32:33], 0, v[122:123]
	v_mul_f32_e32 v35, 0xbfb8aa3b, v34
	v_mul_f32_e32 v20, v20, v35
	v_mul_f32_e32 v16, v16, v35
	v_mul_f32_e32 v21, v21, v35
	v_mul_f32_e32 v17, v17, v35
	v_mul_f32_e32 v22, v22, v35
	v_mul_f32_e32 v18, v18, v35
	v_mul_f32_e32 v23, v23, v35
	v_mul_f32_e32 v19, v19, v35
	v_exp_f32_e32 v20, v20
	v_exp_f32_e32 v16, v16
	v_exp_f32_e32 v21, v21
	v_exp_f32_e32 v17, v17
	v_exp_f32_e32 v22, v22
	v_exp_f32_e32 v18, v18
	v_exp_f32_e32 v23, v23
	v_exp_f32_e32 v19, v19
	v_add_f32_e32 v20, 1.0, v20
	v_add_f32_e32 v35, 1.0, v16
	v_add_f32_e32 v21, 1.0, v21
	v_add_f32_e32 v36, 1.0, v17
	v_add_f32_e32 v22, 1.0, v22
	v_add_f32_e32 v37, 1.0, v18
	v_add_f32_e32 v23, 1.0, v23
	v_add_f32_e32 v38, 1.0, v19
	v_rcp_f32_e32 v16, v20
	v_rcp_f32_e32 v18, v35
	v_rcp_f32_e32 v17, v21
	v_rcp_f32_e32 v19, v36
	v_rcp_f32_e32 v20, v22
	v_rcp_f32_e32 v22, v37
	v_rcp_f32_e32 v21, v23
	v_rcp_f32_e32 v23, v38
	v_mul_f32_e32 v34, v34, v34
	v_pk_mul_f32 v[16:17], v[34:35], v[16:17] op_sel_hi:[0,1]
	v_pk_mul_f32 v[18:19], v[34:35], v[18:19] op_sel_hi:[0,1]
	v_pk_mul_f32 v[20:21], v[34:35], v[20:21] op_sel_hi:[0,1]
	v_pk_mul_f32 v[22:23], v[34:35], v[22:23] op_sel_hi:[0,1]
	v_pk_mul_f32 v[16:17], v[28:29], v[16:17]
	v_pk_mul_f32 v[18:19], v[24:25], v[18:19]
	v_pk_mul_f32 v[20:21], v[30:31], v[20:21]
	v_pk_mul_f32 v[22:23], v[26:27], v[22:23]
	v_cvt_pk_bf16_f32 v16, v16, v17
	v_cvt_pk_bf16_f32 v17, v20, v21
	v_cvt_pk_bf16_f32 v18, v18, v19
	v_cvt_pk_bf16_f32 v19, v22, v23
	global_store_dwordx4 v[32:33], v[16:19], off nt
	s_nop 1
	v_ffbh_u32_e32 v18, v183
	v_min_u32_e32 v18, 32, v18
	v_lshlrev_b64 v[16:17], v18, v[182:183]
	v_min_u32_e32 v16, 1, v16
	v_or_b32_e32 v16, v17, v16
	v_cvt_f32_u32_e32 v16, v16
	v_sub_u32_e32 v18, 32, v18
	v_add_u32_e32 v17, 0xb0, v144
	v_ldexp_f32 v16, v16, v18
	v_mul_f32_e32 v16, 0x33800000, v16
	v_fmamk_f32 v16, v16, 0x3a000000, v154
	v_rsq_f32_e32 v18, v16
	v_mad_i64_i32 v[16:17], s[24:25], v17, s52, v[120:121]
	v_lshl_add_u64 v[16:17], v[16:17], 0, v[122:123]
	v_mul_f32_e32 v19, 0xbfb8aa3b, v18
	v_mul_f32_e32 v4, v4, v19
	v_mul_f32_e32 v0, v0, v19
	v_mul_f32_e32 v5, v5, v19
	v_mul_f32_e32 v1, v1, v19
	v_mul_f32_e32 v6, v6, v19
	v_mul_f32_e32 v2, v2, v19
	v_mul_f32_e32 v7, v7, v19
	v_mul_f32_e32 v3, v3, v19
	v_exp_f32_e32 v4, v4
	v_exp_f32_e32 v0, v0
	v_exp_f32_e32 v5, v5
	v_exp_f32_e32 v1, v1
	v_exp_f32_e32 v6, v6
	v_exp_f32_e32 v2, v2
	v_exp_f32_e32 v7, v7
	v_exp_f32_e32 v3, v3
	v_add_f32_e32 v4, 1.0, v4
	v_add_f32_e32 v19, 1.0, v0
	v_add_f32_e32 v5, 1.0, v5
	v_add_f32_e32 v20, 1.0, v1
	v_add_f32_e32 v6, 1.0, v6
	v_add_f32_e32 v21, 1.0, v2
	v_add_f32_e32 v7, 1.0, v7
	v_add_f32_e32 v22, 1.0, v3
	v_rcp_f32_e32 v0, v4
	v_rcp_f32_e32 v2, v19
	v_rcp_f32_e32 v1, v5
	v_rcp_f32_e32 v3, v20
	v_rcp_f32_e32 v4, v6
	v_rcp_f32_e32 v6, v21
	v_rcp_f32_e32 v5, v7
	v_rcp_f32_e32 v7, v22
	v_mul_f32_e32 v18, v18, v18
	v_pk_mul_f32 v[0:1], v[18:19], v[0:1] op_sel_hi:[0,1]
	v_pk_mul_f32 v[2:3], v[18:19], v[2:3] op_sel_hi:[0,1]
	v_pk_mul_f32 v[4:5], v[18:19], v[4:5] op_sel_hi:[0,1]
	v_pk_mul_f32 v[6:7], v[18:19], v[6:7] op_sel_hi:[0,1]
	v_pk_mul_f32 v[0:1], v[12:13], v[0:1]
	v_pk_mul_f32 v[2:3], v[8:9], v[2:3]
	v_pk_mul_f32 v[4:5], v[14:15], v[4:5]
	v_pk_mul_f32 v[6:7], v[10:11], v[6:7]
	v_cvt_pk_bf16_f32 v0, v0, v1
	v_cvt_pk_bf16_f32 v1, v4, v5
	v_cvt_pk_bf16_f32 v2, v2, v3
	v_cvt_pk_bf16_f32 v3, v6, v7
	global_store_dwordx4 v[16:17], v[0:3], off nt
	s_cbranch_vccnz .LBB0_2165
	s_andn2_b64 vcc, exec, s[0:1]
	s_cbranch_vccnz .LBB0_2164
	s_barrier
	s_branch .LBB0_2164
